# FoX attention loops: s_setprio 1 around each basic-block-local MFMA cluster (QK chain, P.V group), back to 0 after
# baseline (speedup 1.0000x reference)
.LBB0_223:
	s_and_b32 s10, s9, 7
	s_ashr_i32 s11, s9, 6
	s_ashr_i32 s30, s9, 3
	s_xor_b32 s4, s10, 15
	s_mul_i32 s5, s11, 0x1400000
	v_readlane_b32 s16, v255, 48
	s_mul_hi_i32 s1, s11, 0x1400000
	s_add_u32 s5, s16, s5
	v_readlane_b32 s16, v255, 49
	s_addc_u32 s22, s16, s1
	s_lshl_b32 s1, s30, 6
	s_and_b32 s1, s1, 0x1c0
	s_lshl_b32 s16, s1, 1
	s_add_u32 s84, s5, s16
	s_addc_u32 s85, s22, 0
	s_ashr_i32 s31, s30, 31
	s_lshl_b64 s[28:29], s[30:31], 14
	v_readlane_b32 s1, v255, 50
	s_add_u32 s28, s1, s28
	v_readlane_b32 s1, v255, 51
	s_addc_u32 s29, s1, s29
	s_lshl_b64 s[30:31], s[30:31], 2
	v_readlane_b32 s1, v255, 52
	s_add_u32 s96, s1, s30
	v_readlane_b32 s1, v255, 53
	v_mov_b32_e32 v144, v226
	v_mov_b32_e32 v0, v227
	s_addc_u32 s97, s1, s31
	s_lshl_b32 s1, s4, 8
	v_readlane_b32 s17, v251, 7
	s_add_i32 s82, s1, s17
	v_and_b32_e32 v149, 31, v144
	v_ashrrev_i32_e32 v18, 5, v144
	s_mul_i32 s23, s82, 0x1400
	v_mul_u32_u24_e32 v0, 0xa00, v149
	s_mul_hi_u32 s17, s82, 0x1400
	s_add_u32 s30, s84, s23
	v_lshl_add_u32 v0, v18, 3, v0
	s_addc_u32 s31, s85, s17
	v_add_u32_e32 v2, 16, v0
	v_mov_b32_e32 v3, v1
	s_mov_b32 s83, s37
	v_lshl_add_u64 v[20:21], v[0:1], 1, s[30:31]
	v_lshl_add_u64 v[24:25], v[2:3], 1, s[30:31]
	v_add_u32_e32 v2, 32, v0
	v_add_u32_e32 v0, 48, v0
	v_lshl_add_u64 v[26:27], v[2:3], 1, s[30:31]
	v_lshl_add_u64 v[28:29], v[0:1], 1, s[30:31]
	s_lshl_b64 s[30:31], s[82:83], 2
	v_lshlrev_b32_e32 v146, 2, v18
	s_add_u32 s30, s28, s30
	s_addc_u32 s31, s29, s31
	v_ashrrev_i32_e32 v147, 31, v146
	v_lshl_add_u64 v[14:15], v[146:147], 2, s[30:31]
	global_load_dwordx4 v[140:143], v[20:21], off offset:2048
	global_load_dwordx4 v[136:139], v[24:25], off offset:2048
	global_load_dwordx4 v[132:135], v[26:27], off offset:2048
	global_load_dwordx4 v[128:131], v[28:29], off offset:2048
	global_load_dwordx4 v[2:5], v[14:15], off
	global_load_dwordx4 v[6:9], v[14:15], off offset:32
	global_load_dwordx4 v[10:13], v[14:15], off offset:64
	s_nop 0
	global_load_dwordx4 v[14:17], v[14:15], off offset:96
	s_nop 0
	global_load_dwordx4 v[20:23], v[20:21], off offset:3072
	v_cmp_gt_i32_e64 s[42:43], v146, v149
	v_cmp_lt_i32_e64 s[44:45], v146, v149
	v_cmp_lt_i32_e32 vcc, v219, v213
	s_setprio 1
	s_waitcnt vmcnt(0)
	v_mfma_f32_32x32x16_bf16 v[2:17], v[20:23], v[140:143], v[2:17]
	global_load_dwordx4 v[20:23], v[24:25], off offset:3072
	s_waitcnt vmcnt(0)
	v_mfma_f32_32x32x16_bf16 v[2:17], v[20:23], v[136:139], v[2:17]
	global_load_dwordx4 v[20:23], v[26:27], off offset:3072
	s_waitcnt vmcnt(0)
	v_mfma_f32_32x32x16_bf16 v[2:17], v[20:23], v[132:135], v[2:17]
	global_load_dwordx4 v[20:23], v[28:29], off offset:3072
	s_waitcnt vmcnt(0)
	v_mfma_f32_32x32x16_bf16 v[2:17], v[20:23], v[128:131], v[2:17]
	s_setprio 0
	s_nop 11
	v_max_f32_e32 v0, v2, v2
	v_max_f32_e32 v0, 0xff800000, v0
	v_cndmask_b32_e64 v0, v0, v220, s[42:43]
	v_max_f32_e32 v2, v3, v3
	v_max_f32_e32 v2, v0, v2
	v_cndmask_b32_e64 v0, v0, v2, s[44:45]
	v_or_b32_e32 v2, 2, v146
	v_cmp_gt_i32_e64 s[46:47], v2, v149
	v_max_f32_e32 v2, v4, v4
	v_max_f32_e32 v2, v0, v2
	v_cndmask_b32_e64 v0, v2, v0, s[46:47]
	v_or_b32_e32 v2, 3, v146
	v_cmp_gt_i32_e64 s[48:49], v2, v149
	v_max_f32_e32 v2, v5, v5
	v_max_f32_e32 v2, v0, v2
	v_cndmask_b32_e64 v0, v2, v0, s[48:49]
	v_add_u32_e32 v2, 8, v146
	v_cmp_gt_i32_e64 s[50:51], v2, v149
	v_max_f32_e32 v2, v6, v6
	v_max_f32_e32 v2, v0, v2
	v_cndmask_b32_e64 v0, v2, v0, s[50:51]
	v_add_u32_e32 v2, 9, v146
	v_cmp_gt_i32_e64 s[52:53], v2, v149
	v_max_f32_e32 v2, v0, v0
	v_max_f32_e32 v3, v7, v7
	v_max_f32_e32 v2, v2, v3
	v_cndmask_b32_e64 v0, v2, v0, s[52:53]
	v_add_u32_e32 v2, 10, v146
	v_cmp_gt_i32_e64 s[54:55], v2, v149
	v_max_f32_e32 v2, v0, v0
	v_max_f32_e32 v3, v8, v8
	v_max_f32_e32 v2, v2, v3
	v_cndmask_b32_e64 v0, v2, v0, s[54:55]
	v_add_u32_e32 v2, 11, v146
	v_cmp_gt_i32_e64 s[56:57], v2, v149
	v_max_f32_e32 v2, v0, v0
	v_max_f32_e32 v3, v9, v9
	v_max_f32_e32 v2, v2, v3
	v_cndmask_b32_e64 v0, v2, v0, s[56:57]
	v_add_u32_e32 v2, 16, v146
	v_cmp_gt_i32_e64 s[58:59], v2, v149
	v_max_f32_e32 v2, v0, v0
	v_max_f32_e32 v3, v10, v10
	v_max_f32_e32 v2, v2, v3
	v_cndmask_b32_e64 v0, v2, v0, s[58:59]
	v_add_u32_e32 v2, 17, v146
	v_cmp_gt_i32_e64 s[60:61], v2, v149
	v_max_f32_e32 v2, v0, v0
	v_max_f32_e32 v3, v11, v11
	v_max_f32_e32 v2, v2, v3
	v_cndmask_b32_e64 v0, v2, v0, s[60:61]
	v_add_u32_e32 v2, 18, v146
	v_cmp_gt_i32_e64 s[62:63], v2, v149
	v_max_f32_e32 v2, v0, v0
	v_max_f32_e32 v3, v12, v12
	v_max_f32_e32 v2, v2, v3
	v_cndmask_b32_e64 v0, v2, v0, s[62:63]
	v_add_u32_e32 v2, 19, v146
	v_cmp_gt_i32_e64 s[64:65], v2, v149
	v_max_f32_e32 v2, v0, v0
	v_max_f32_e32 v3, v13, v13
	v_max_f32_e32 v2, v2, v3
	v_cndmask_b32_e64 v0, v2, v0, s[64:65]
	v_add_u32_e32 v2, 24, v146
	v_cmp_gt_i32_e64 s[66:67], v2, v149
	v_max_f32_e32 v2, v0, v0
	v_max_f32_e32 v3, v14, v14
	v_max_f32_e32 v2, v2, v3
	v_cndmask_b32_e64 v0, v2, v0, s[66:67]
	v_add_u32_e32 v2, 25, v146
	v_cmp_gt_i32_e64 s[68:69], v2, v149
	v_max_f32_e32 v2, v0, v0
	v_max_f32_e32 v3, v15, v15
	v_max_f32_e32 v2, v2, v3
	v_cndmask_b32_e64 v0, v2, v0, s[68:69]
	v_add_u32_e32 v2, 26, v146
	v_cmp_gt_i32_e64 s[70:71], v2, v149
	v_max_f32_e32 v2, v0, v0
	v_max_f32_e32 v3, v16, v16
	v_max_f32_e32 v2, v2, v3
	v_cndmask_b32_e64 v0, v2, v0, s[70:71]
	v_add_u32_e32 v2, 27, v146
	v_cmp_gt_i32_e64 s[72:73], v2, v149
	v_max_f32_e32 v2, v0, v0
	v_max_f32_e32 v3, v17, v17
	v_max_f32_e32 v2, v2, v3
	v_cndmask_b32_e64 v0, v2, v0, s[72:73]
	v_cndmask_b32_e32 v2, v211, v219, vcc
	v_lshlrev_b32_e32 v147, 2, v2
	ds_bpermute_b32 v2, v147, v0
	v_max_f32_e32 v0, v0, v0
	v_and_b32_e32 v3, 0xffff0000, v140
	v_mul_f32_e32 v3, v3, v3
	v_cmp_lt_i32_e32 vcc, v250, v213
	s_waitcnt lgkmcnt(0)
	v_max_f32_e32 v2, v2, v2
	v_max_f32_e32 v0, v0, v2
	v_lshlrev_b32_e32 v2, 16, v140
	v_fmac_f32_e32 v3, v2, v2
	v_lshlrev_b32_e32 v2, 16, v141
	v_fmac_f32_e32 v3, v2, v2
	v_and_b32_e32 v2, 0xffff0000, v141
	v_fmac_f32_e32 v3, v2, v2
	v_lshlrev_b32_e32 v2, 16, v142
	v_fmac_f32_e32 v3, v2, v2
	v_and_b32_e32 v2, 0xffff0000, v142
	v_fmac_f32_e32 v3, v2, v2
	v_lshlrev_b32_e32 v2, 16, v143
	v_fmac_f32_e32 v3, v2, v2
	v_and_b32_e32 v2, 0xffff0000, v143
	v_fmac_f32_e32 v3, v2, v2
	v_lshlrev_b32_e32 v2, 16, v136
	v_fmac_f32_e32 v3, v2, v2
	v_and_b32_e32 v2, 0xffff0000, v136
	v_fmac_f32_e32 v3, v2, v2
	v_lshlrev_b32_e32 v2, 16, v137
	v_fmac_f32_e32 v3, v2, v2
	v_and_b32_e32 v2, 0xffff0000, v137
	v_fmac_f32_e32 v3, v2, v2
	v_lshlrev_b32_e32 v2, 16, v138
	v_fmac_f32_e32 v3, v2, v2
	v_and_b32_e32 v2, 0xffff0000, v138
	v_fmac_f32_e32 v3, v2, v2
	v_lshlrev_b32_e32 v2, 16, v139
	v_fmac_f32_e32 v3, v2, v2
	v_and_b32_e32 v2, 0xffff0000, v139
	v_fmac_f32_e32 v3, v2, v2
	v_lshlrev_b32_e32 v2, 16, v132
	v_fmac_f32_e32 v3, v2, v2
	v_and_b32_e32 v2, 0xffff0000, v132
	v_fmac_f32_e32 v3, v2, v2
	v_lshlrev_b32_e32 v2, 16, v133
	v_fmac_f32_e32 v3, v2, v2
	v_and_b32_e32 v2, 0xffff0000, v133
	v_fmac_f32_e32 v3, v2, v2
	v_lshlrev_b32_e32 v2, 16, v134
	v_fmac_f32_e32 v3, v2, v2
	v_and_b32_e32 v2, 0xffff0000, v134
	v_fmac_f32_e32 v3, v2, v2
	v_lshlrev_b32_e32 v2, 16, v135
	v_fmac_f32_e32 v3, v2, v2
	v_and_b32_e32 v2, 0xffff0000, v135
	v_fmac_f32_e32 v3, v2, v2
	v_lshlrev_b32_e32 v2, 16, v128
	v_fmac_f32_e32 v3, v2, v2
	v_and_b32_e32 v2, 0xffff0000, v128
	v_fmac_f32_e32 v3, v2, v2
	v_lshlrev_b32_e32 v2, 16, v129
	v_fmac_f32_e32 v3, v2, v2
	v_and_b32_e32 v2, 0xffff0000, v129
	v_fmac_f32_e32 v3, v2, v2
	v_lshlrev_b32_e32 v2, 16, v130
	v_fmac_f32_e32 v3, v2, v2
	v_and_b32_e32 v2, 0xffff0000, v130
	v_fmac_f32_e32 v3, v2, v2
	v_lshlrev_b32_e32 v2, 16, v131
	v_fmac_f32_e32 v3, v2, v2
	v_and_b32_e32 v2, 0xffff0000, v131
	v_fmac_f32_e32 v3, v2, v2
	global_load_dword v2, v1, s[96:97]
	v_add_f32_e32 v161, 0xc2200000, v0
	ds_bpermute_b32 v0, v147, v3
	s_waitcnt lgkmcnt(0)
	v_add_f32_e32 v0, v3, v0
	s_waitcnt vmcnt(0)
	v_mul_f32_e32 v0, v2, v0
	v_sqrt_f32_e32 v0, v0
	v_cndmask_b32_e32 v2, v211, v250, vcc
	v_lshlrev_b32_e32 v156, 2, v2
	v_cmp_lt_i32_e32 vcc, v221, v213
	v_fmamk_f32 v0, v0, 0xbf8020c5, v161
	v_add_f32_e32 v0, 0xbc23d70a, v0
	ds_bpermute_b32 v2, v156, v0
	s_waitcnt lgkmcnt(0)
	v_max_f32_e32 v2, v2, v2
	v_min_f32_e32 v0, v0, v2
	v_cndmask_b32_e32 v2, v211, v221, vcc
	v_lshlrev_b32_e32 v157, 2, v2
	ds_bpermute_b32 v2, v157, v0
	v_cmp_lt_i32_e32 vcc, v212, v213
	s_waitcnt lgkmcnt(0)
	v_max_f32_e32 v2, v2, v2
	v_min_f32_e32 v0, v0, v2
	v_cndmask_b32_e32 v2, v211, v212, vcc
	v_lshlrev_b32_e32 v158, 2, v2
	ds_bpermute_b32 v2, v158, v0
	v_cmp_lt_i32_e32 vcc, v210, v213
	s_waitcnt lgkmcnt(0)
	v_max_f32_e32 v2, v2, v2
	v_min_f32_e32 v0, v0, v2
	v_cndmask_b32_e32 v2, v211, v210, vcc
	v_lshlrev_b32_e32 v159, 2, v2
	ds_bpermute_b32 v2, v159, v0
	v_cmp_lt_i32_e32 vcc, v218, v213
	s_waitcnt lgkmcnt(0)
	v_max_f32_e32 v2, v2, v2
	v_min_f32_e32 v0, v0, v2
	v_cndmask_b32_e32 v2, v211, v218, vcc
	v_lshlrev_b32_e32 v160, 2, v2
	ds_bpermute_b32 v2, v160, v0
	v_cmp_eq_u32_e32 vcc, 0, v144
	s_and_saveexec_b64 s[30:31], vcc
	s_cbranch_execz .LBB0_225
	s_waitcnt lgkmcnt(0)
	v_max_f32_e32 v2, v2, v2
	v_max_f32_e32 v0, v0, v0
	v_readlane_b32 s17, v251, 13
	v_min_f32_e32 v0, v0, v2
	s_nop 0
	v_mov_b32_e32 v2, s17
	ds_write_b32 v2, v0

.LBB0_227:
	s_or_b64 exec, exec, s[30:31]
	s_waitcnt lgkmcnt(6)
	v_max_f32_e32 v6, v6, v6
	v_max_f32_e32 v0, v0, v0
	v_min_f32_e32 v0, v0, v6
	s_waitcnt lgkmcnt(4)
	v_min3_f32 v0, v0, v3, v4
	s_add_u32 s5, s5, s16
	s_waitcnt lgkmcnt(2)
	v_min3_f32 v0, v0, v5, v7
	s_addc_u32 s17, s22, 0
	s_waitcnt lgkmcnt(0)
	v_min3_f32 v3, v0, v8, v9
	s_add_u32 s30, s5, 0x1000
	v_ashrrev_i32_e32 v148, 3, v144
	v_readlane_b32 s5, v251, 12
	s_waitcnt vmcnt(0)
	v_cmp_ge_f32_e32 vcc, v2, v3
	s_addc_u32 s31, s17, 0
	v_add_u32_e32 v0, s5, v148
	s_movk_i32 s5, 0xa00
	v_mul_lo_u32 v0, v0, s5
	s_ff1_i32_b64 s5, vcc
	s_lshl_b32 s4, s4, 2
	s_min_u32 s74, s5, s4
	s_cmp_lg_u64 vcc, 0
	v_xor_b32_e32 v4, v148, v144
	s_cselect_b32 s17, s74, 0
	v_lshlrev_b32_e32 v4, 3, v4
	s_lshl_b32 s38, s17, 6
	s_mul_i32 s40, s17, 0x50000
	v_and_or_b32 v0, v4, 56, v0
	s_add_u32 s4, s84, s40
	s_addc_u32 s5, s85, 0
	v_lshlrev_b64 v[64:65], 1, v[0:1]
	s_waitcnt lgkmcnt(0)
	s_barrier
	v_lshl_add_u64 v[2:3], s[4:5], 0, v[64:65]
	s_mov_b64 s[78:79], 0xc00
	v_lshl_add_u64 v[2:3], v[2:3], 0, s[78:79]
	s_mov_b32 s4, m0
	s_mov_b32 m0, s0
	s_nop 0
	global_load_lds_dwordx4 v[2:3], off
	s_mov_b32 m0, s4
	s_add_u32 s4, s30, s40
	s_addc_u32 s5, s31, 0
	v_lshl_add_u64 v[2:3], s[4:5], 0, v[64:65]
	s_mov_b32 s4, m0
	s_mov_b32 m0, s27
	s_nop 0
	global_load_lds_dwordx4 v[2:3], off
	s_mov_b32 m0, s4
	s_lshl_b32 s36, s17, 8
	s_add_u32 s4, s28, s36
	v_ashrrev_i32_e32 v145, 31, v144
	s_addc_u32 s5, s29, 0
	v_lshlrev_b64 v[6:7], 2, v[144:145]
	v_lshl_add_u64 v[2:3], s[4:5], 0, v[6:7]
	s_add_i32 s26, s0, 0x18000
	s_mov_b32 s4, m0
	s_mov_b32 m0, s26
	s_nop 0
	global_load_lds_dword v[2:3], off
	s_mov_b32 m0, s4
	s_add_i32 s4, s38, 64
	s_add_i32 s22, s40, 0x50000
	s_mul_hi_u32 s39, s4, 0x1400
	s_add_u32 s4, s84, s22
	s_addc_u32 s5, s85, s39
	v_lshl_add_u64 v[4:5], s[4:5], 0, v[64:65]
	v_lshl_add_u64 v[4:5], v[4:5], 0, s[78:79]
	s_add_i32 s23, s0, 0x2000
	s_mov_b32 s4, m0
	s_mov_b32 m0, s23
	s_nop 0
	global_load_lds_dwordx4 v[4:5], off
	s_mov_b32 m0, s4
	s_add_u32 s4, s30, s22
	s_addc_u32 s5, s31, s39
	v_lshl_add_u64 v[4:5], s[4:5], 0, v[64:65]
	s_add_i32 s22, s0, 0xc000
	s_mov_b32 s4, m0
	s_mov_b32 m0, s22
	s_nop 0
	global_load_lds_dwordx4 v[4:5], off
	s_mov_b32 m0, s4
	v_lshl_add_u64 v[4:5], v[2:3], 0, s[24:25]
	s_add_i32 s39, s0, 0x18100
	s_mov_b32 s4, m0
	s_mov_b32 m0, s39
	s_nop 0
	global_load_lds_dword v[4:5], off
	s_mov_b32 m0, s4
	s_addk_i32 s38, 0x80
	s_add_i32 s40, s40, 0xa0000
	s_mul_hi_u32 s75, s38, 0x1400
	s_add_u32 s4, s84, s40
	s_addc_u32 s5, s85, s75
	v_lshl_add_u64 v[4:5], s[4:5], 0, v[64:65]
	v_lshl_add_u64 v[4:5], v[4:5], 0, s[78:79]
	s_add_i32 s38, s0, 0x4000
	s_mov_b32 s4, m0
	s_mov_b32 m0, s38
	s_nop 0
	global_load_lds_dwordx4 v[4:5], off
	s_mov_b32 m0, s4
	s_add_u32 s4, s30, s40
	s_addc_u32 s5, s31, s75
	v_lshl_add_u64 v[4:5], s[4:5], 0, v[64:65]
	s_add_i32 s5, s0, 0x10000
	s_mov_b32 s4, m0
	s_mov_b32 m0, s5
	s_nop 0
	global_load_lds_dwordx4 v[4:5], off
	s_mov_b32 m0, s4
	v_lshl_add_u64 v[2:3], v[2:3], 0, s[86:87]
	s_add_i32 s4, s0, 0x18200
	s_mov_b32 s40, m0
	s_mov_b32 m0, s4
	s_nop 0
	global_load_lds_dword v[2:3], off
	s_mov_b32 m0, s40
	v_lshlrev_b32_e32 v166, 4, v18
	v_readlane_b32 s40, v251, 14
	s_waitcnt vmcnt(3) lgkmcnt(0)
	s_barrier
	v_lshlrev_b32_e32 v167, 7, v149
	v_add_u32_e32 v72, 0, v167
	v_add_u32_e32 v0, s40, v166
	ds_read_b128 v[96:99], v0
	ds_read_b128 v[100:103], v0 offset:32
	ds_read_b128 v[104:107], v0 offset:64
	ds_read_b128 v[108:111], v0 offset:96
	v_bitop3_b32 v0, v18, v144, 7 bitop3:0x78
	v_lshlrev_b32_e32 v168, 4, v0
	v_add_u32_e32 v0, v72, v168
	ds_read_b128 v[2:5], v0
	v_add_u32_e32 v0, 2, v18
	v_bitop3_b32 v0, v0, v144, 7 bitop3:0x78
	v_lshlrev_b32_e32 v171, 4, v0
	v_add_u32_e32 v0, v72, v171
	s_setprio 1
	s_waitcnt lgkmcnt(0)
	v_mfma_f32_32x32x16_bf16 v[96:111], v[2:5], v[140:143], v[96:111]
	ds_read_b128 v[2:5], v0
	v_add_u32_e32 v0, 4, v18
	v_bitop3_b32 v0, v0, v144, 7 bitop3:0x78
	v_lshlrev_b32_e32 v169, 4, v0
	v_add_u32_e32 v0, v72, v169
	v_bfe_u32 v163, v144, 2, 2
	s_lshr_b32 s40, s82, 6
	s_waitcnt lgkmcnt(0)
	v_mfma_f32_32x32x16_bf16 v[96:111], v[2:5], v[136:139], v[96:111]
	ds_read_b128 v[2:5], v0
	v_add_u32_e32 v0, 6, v18
	v_bitop3_b32 v0, v0, v144, 7 bitop3:0x78
	v_lshlrev_b32_e32 v170, 4, v0
	v_add_u32_e32 v0, v72, v170
	v_bfe_u32 v164, v144, 4, 1
	v_and_b32_e32 v165, 3, v144
	s_waitcnt lgkmcnt(0)
	v_mfma_f32_32x32x16_bf16 v[96:111], v[2:5], v[132:135], v[96:111]
	ds_read_b128 v[2:5], v0
	v_or_b32_e32 v162, v146, v163
	s_mov_b32 s83, 0
	s_mov_b64 s[86:87], 0xc00
	v_lshl_add_u64 v[152:153], s[30:31], 0, v[64:65]
	v_lshl_add_u64 v[154:155], s[28:29], 0, v[6:7]
	s_cmp_ge_u32 s17, s40
	s_waitcnt lgkmcnt(0)
	v_mfma_f32_32x32x16_bf16 v[96:111], v[2:5], v[128:131], v[96:111]
	s_setprio 0
	v_lshl_add_u64 v[2:3], s[84:85], 0, v[64:65]
	v_lshl_add_u64 v[150:151], v[2:3], 0, s[78:79]
	s_cbranch_scc1 .LBB0_252
	v_lshlrev_b32_e32 v0, 1, v164
	v_lshrrev_b32_e32 v2, 1, v165
	v_or_b32_e32 v3, v0, v2
	v_bitop3_b32 v0, v0, v162, v2 bitop3:0x36
	v_lshlrev_b32_e32 v4, 3, v144
	v_lshlrev_b32_e32 v76, 4, v0
	v_bitop3_b32 v0, v3, v162, 4 bitop3:0x36
	v_lshl_add_u64 v[2:3], v[154:155], 0, s[36:37]
	s_mov_b64 s[78:79], 0x300
	v_and_b32_e32 v4, 8, v4
	v_lshl_add_u64 v[66:67], v[2:3], 0, s[78:79]
	v_mad_u64_u32 v[2:3], s[78:79], s17, v223, v[152:153]
	s_mov_b64 s[90:91], 0xf0000
	v_add_u32_e32 v4, 0, v4
	v_add_lshl_u32 v5, v146, v163, 7
	v_lshl_add_u64 v[68:69], v[2:3], 0, s[90:91]
	v_mad_u64_u32 v[2:3], s[78:79], s17, v223, v[150:151]
	v_mov_b32_e32 v14, v1
	v_mov_b32_e32 v15, v1
	v_readlane_b32 s77, v251, 13
	v_lshlrev_b32_e32 v77, 4, v0
	v_lshl_add_u32 v78, v162, 7, v4
	v_add3_u32 v79, v5, v4, s21
	v_lshl_add_u64 v[70:71], v[2:3], 0, s[90:91]
	v_mov_b32_e32 v0, v1
	v_mov_b32_e32 v2, v1
	v_mov_b32_e32 v3, v1
	v_mov_b32_e32 v4, v1
	v_mov_b32_e32 v5, v1
	v_mov_b32_e32 v6, v1
	v_mov_b32_e32 v7, v1
	v_mov_b32_e32 v8, v1
	v_mov_b32_e32 v9, v1
	v_mov_b32_e32 v10, v1
	v_mov_b32_e32 v11, v1
	v_mov_b32_e32 v12, v1
	v_mov_b32_e32 v13, v1
	v_mov_b64_e32 v[94:95], v[14:15]
	v_cmp_gt_u32_e64 s[74:75], 32, v144
	v_lshl_add_u32 v73, v149, 2, s77
	v_lshl_add_u32 v74, v146, 2, s77
	v_add_u32_e32 v75, s19, v166
	v_mov_b32_e32 v16, v1
	v_mov_b32_e32 v17, v1
	v_mov_b32_e32 v18, v1
	v_mov_b32_e32 v19, v1
	v_mov_b32_e32 v20, v1
	v_mov_b32_e32 v21, v1
	v_mov_b32_e32 v22, v1
	v_mov_b32_e32 v23, v1
	v_mov_b32_e32 v24, v1
	v_mov_b32_e32 v25, v1
	v_mov_b32_e32 v26, v1
	v_mov_b32_e32 v27, v1
	v_mov_b32_e32 v28, v1
	v_mov_b32_e32 v29, v1
	v_mov_b32_e32 v30, v1
	v_mov_b32_e32 v31, v1
	v_mov_b32_e32 v32, v1
	v_mov_b32_e32 v33, v1
	v_mov_b32_e32 v34, v1
	v_mov_b32_e32 v35, v1
	v_mov_b32_e32 v36, v1
	v_mov_b32_e32 v37, v1
	v_mov_b32_e32 v38, v1
	v_mov_b32_e32 v39, v1
	v_mov_b32_e32 v40, v1
	v_mov_b32_e32 v41, v1
	v_mov_b32_e32 v42, v1
	v_mov_b32_e32 v43, v1
	v_mov_b32_e32 v44, v1
	v_mov_b32_e32 v45, v1
	v_mov_b32_e32 v46, v1
	v_mov_b32_e32 v47, v1
	s_mov_b32 s36, 0
	v_mov_b32_e32 v172, 0xff800000
	v_mov_b64_e32 v[92:93], v[12:13]
	v_mov_b64_e32 v[90:91], v[10:11]
	v_mov_b64_e32 v[88:89], v[8:9]
	v_mov_b64_e32 v[86:87], v[6:7]
	v_mov_b64_e32 v[84:85], v[4:5]
	v_mov_b64_e32 v[82:83], v[2:3]
	v_mov_b64_e32 v[80:81], v[0:1]

.LBB0_231:
	v_lshl_add_u32 v0, s36, 13, v72
	s_or_b32 s77, s36, s95
	v_add_u32_e32 v2, v0, v168
	v_lshl_add_u32 v6, s77, 8, v75
	ds_read_b128 v[2:5], v2 offset:4096
	ds_read_b128 v[48:51], v6 offset:128
	ds_read_b128 v[52:55], v6 offset:160
	ds_read_b128 v[56:59], v6 offset:192
	ds_read_b128 v[60:63], v6 offset:224
	v_add_u32_e32 v6, v0, v171
	ds_read_b128 v[6:9], v6 offset:4096
	s_setprio 1
	s_waitcnt lgkmcnt(1)
	v_mfma_f32_32x32x16_bf16 v[48:63], v[2:5], v[140:143], v[48:63]
	v_add_u32_e32 v2, v0, v169
	ds_read_b128 v[2:5], v2 offset:4096
	v_add_u32_e32 v0, v0, v170
	v_max_f32_e32 v10, v96, v96
	s_waitcnt lgkmcnt(1)
	v_mfma_f32_32x32x16_bf16 v[48:63], v[6:9], v[136:139], v[48:63]
	ds_read_b128 v[6:9], v0 offset:4096
	v_max_f32_e32 v0, v97, v97
	v_max_f32_e32 v0, v10, v0
	v_max3_f32 v0, v0, v98, v99
	v_max3_f32 v0, v0, v100, v101
	v_max3_f32 v0, v0, v102, v103
	v_max3_f32 v0, v0, v104, v105
	s_waitcnt lgkmcnt(1)
	v_mfma_f32_32x32x16_bf16 v[48:63], v[2:5], v[132:135], v[48:63]
	v_max3_f32 v0, v0, v106, v107
	v_max3_f32 v0, v0, v108, v109
	v_max3_f32 v0, v0, v110, v111
	ds_bpermute_b32 v2, v147, v0
	s_waitcnt lgkmcnt(0)
	v_max_f32_e32 v2, v2, v2
	v_mfma_f32_32x32x16_bf16 v[48:63], v[6:9], v[128:131], v[48:63]
	s_setprio 0
	v_max_f32_e32 v0, v0, v2
	v_cmp_ge_f32_e32 vcc, v0, v161
	s_cbranch_vccz .LBB0_236
	v_add_f32_e32 v2, 0x41000000, v172
	v_cmp_gt_f32_e32 vcc, v0, v2
	s_cbranch_vccz .LBB0_237
	v_max_f32_e32 v0, v0, v0
	v_max_f32_e32 v2, v172, v172
	v_max_f32_e32 v0, v2, v0
	s_and_saveexec_b64 s[78:79], s[74:75]
	s_cbranch_execz .LBB0_235
	v_sub_f32_e32 v2, v172, v0
	v_exp_f32_e32 v2, v2
	ds_write_b32 v73, v2

.LBB0_238:
	v_sub_f32_e32 v2, v96, v0
	v_sub_f32_e32 v3, v97, v0
	v_sub_f32_e32 v4, v98, v0
	v_sub_f32_e32 v5, v99, v0
	v_sub_f32_e32 v6, v100, v0
	v_sub_f32_e32 v7, v101, v0
	v_sub_f32_e32 v8, v102, v0
	v_sub_f32_e32 v9, v103, v0
	v_exp_f32_e32 v2, v2
	v_exp_f32_e32 v3, v3
	v_exp_f32_e32 v4, v4
	v_exp_f32_e32 v5, v5
	v_exp_f32_e32 v6, v6
	v_exp_f32_e32 v7, v7
	v_exp_f32_e32 v8, v8
	v_exp_f32_e32 v9, v9
	v_lshl_add_u32 v98, s36, 14, v78
	v_add_u32_e32 v99, v98, v76
	v_cvt_pk_bf16_f32 v2, v2, v3
	v_cvt_pk_bf16_f32 v3, v4, v5
	v_cvt_pk_bf16_f32 v4, v6, v7
	v_cvt_pk_bf16_f32 v5, v8, v9
	ds_read_b64_tr_b16 v[6:7], v99 offset:32768
	ds_read_b64_tr_b16 v[8:9], v99 offset:33792
	v_add_u32_e32 v98, v98, v77
	s_waitcnt lgkmcnt(0)
	v_mfma_f32_32x32x16_bf16 v[16:31], v[2:5], v[6:9], v[16:31]
	ds_read_b64_tr_b16 v[6:7], v98 offset:32768
	ds_read_b64_tr_b16 v[8:9], v98 offset:33792
	v_sub_f32_e32 v10, v104, v0
	v_sub_f32_e32 v11, v105, v0
	v_sub_f32_e32 v12, v106, v0
	v_sub_f32_e32 v13, v107, v0
	v_sub_f32_e32 v14, v108, v0
	v_sub_f32_e32 v15, v109, v0
	v_sub_f32_e32 v96, v110, v0
	v_sub_f32_e32 v97, v111, v0
	v_exp_f32_e32 v10, v10
	v_exp_f32_e32 v11, v11
	v_exp_f32_e32 v12, v12
	v_exp_f32_e32 v13, v13
	v_exp_f32_e32 v14, v14
	v_exp_f32_e32 v15, v15
	v_exp_f32_e32 v96, v96
	v_exp_f32_e32 v97, v97
	s_mov_b32 s77, s76
	s_setprio 1
	s_waitcnt lgkmcnt(0)
	v_mfma_f32_32x32x16_bf16 v[32:47], v[2:5], v[6:9], v[32:47]
	s_mov_b32 s78, s76
	s_mov_b32 s79, s76
	v_mov_b64_e32 v[6:7], s[76:77]
	v_mov_b64_e32 v[8:9], s[78:79]
	s_nop 1
	v_mfma_f32_32x32x16_bf16 v[80:95], v[2:5], v[6:9], v[80:95]
	v_cvt_pk_bf16_f32 v2, v10, v11
	v_cvt_pk_bf16_f32 v3, v12, v13
	v_cvt_pk_bf16_f32 v4, v14, v15
	v_cvt_pk_bf16_f32 v5, v96, v97
	ds_read_b64_tr_b16 v[10:11], v99 offset:34816
	ds_read_b64_tr_b16 v[12:13], v99 offset:35840
	s_waitcnt lgkmcnt(0)
	v_mfma_f32_32x32x16_bf16 v[16:31], v[2:5], v[10:13], v[16:31]
	ds_read_b64_tr_b16 v[10:11], v98 offset:34816
	ds_read_b64_tr_b16 v[12:13], v98 offset:35840
	s_waitcnt lgkmcnt(0)
	v_mfma_f32_32x32x16_bf16 v[32:47], v[2:5], v[10:13], v[32:47]
	v_mfma_f32_32x32x16_bf16 v[80:95], v[2:5], v[6:9], v[80:95]
	s_setprio 0
.LBB0_239:
	s_add_i32 s77, s36, 1
	s_and_b32 s83, s77, 3
	v_lshl_add_u32 v10, s83, 13, v72
	s_or_b32 s77, s83, s95
	v_add_u32_e32 v2, v10, v168
	v_lshl_add_u32 v6, s77, 8, v75
	ds_read_b128 v[2:5], v2
	ds_read_b128 v[96:99], v6
	ds_read_b128 v[100:103], v6 offset:32
	ds_read_b128 v[104:107], v6 offset:64
	ds_read_b128 v[108:111], v6 offset:96
	v_add_u32_e32 v6, v10, v171
	ds_read_b128 v[6:9], v6
	s_setprio 1
	s_waitcnt lgkmcnt(1)
	v_mfma_f32_32x32x16_bf16 v[96:111], v[2:5], v[140:143], v[96:111]
	v_add_u32_e32 v2, v10, v169
	ds_read_b128 v[2:5], v2
	v_max_f32_e32 v11, v48, v48
	s_waitcnt lgkmcnt(1)
	v_mfma_f32_32x32x16_bf16 v[96:111], v[6:9], v[136:139], v[96:111]
	v_add_u32_e32 v6, v10, v170
	ds_read_b128 v[6:9], v6
	v_max_f32_e32 v10, v49, v49
	v_max_f32_e32 v10, v11, v10
	v_max3_f32 v10, v10, v50, v51
	v_max3_f32 v10, v10, v52, v53
	s_waitcnt lgkmcnt(1)
	v_mfma_f32_32x32x16_bf16 v[96:111], v[2:5], v[132:135], v[96:111]
	v_max3_f32 v2, v10, v54, v55
	v_max3_f32 v2, v2, v56, v57
	v_max3_f32 v2, v2, v58, v59
	v_max3_f32 v2, v2, v60, v61
	v_max3_f32 v2, v2, v62, v63
	ds_bpermute_b32 v3, v147, v2
	s_waitcnt lgkmcnt(0)
	v_max_f32_e32 v3, v3, v3
	v_mfma_f32_32x32x16_bf16 v[96:111], v[6:9], v[128:131], v[96:111]
	s_setprio 0
	v_max_f32_e32 v2, v2, v3
	v_cmp_ge_f32_e32 vcc, v2, v161
	s_cbranch_vccz .LBB0_244
	v_add_f32_e32 v3, 0x41000000, v0
	v_cmp_gt_f32_e32 vcc, v2, v3
	s_cbranch_vccz .LBB0_245
	v_max_f32_e32 v2, v2, v2
	v_max_f32_e32 v3, v0, v0
	v_max_f32_e32 v172, v3, v2
	s_and_saveexec_b64 s[78:79], s[74:75]
	s_cbranch_execz .LBB0_243
	v_sub_f32_e32 v0, v0, v172
	v_exp_f32_e32 v0, v0
	ds_write_b32 v73, v0

.LBB0_246:
	v_sub_f32_e32 v9, v56, v172
	v_sub_f32_e32 v0, v48, v172
	v_sub_f32_e32 v2, v49, v172
	v_exp_f32_e32 v10, v9
	v_sub_f32_e32 v9, v57, v172
	v_exp_f32_e32 v0, v0
	v_exp_f32_e32 v2, v2
	v_exp_f32_e32 v11, v9
	v_sub_f32_e32 v9, v58, v172
	v_sub_f32_e32 v3, v50, v172
	v_sub_f32_e32 v4, v51, v172
	v_sub_f32_e32 v5, v52, v172
	v_sub_f32_e32 v6, v53, v172
	v_sub_f32_e32 v7, v54, v172
	v_sub_f32_e32 v8, v55, v172
	v_exp_f32_e32 v12, v9
	v_sub_f32_e32 v9, v59, v172
	v_exp_f32_e32 v3, v3
	v_exp_f32_e32 v4, v4
	v_exp_f32_e32 v5, v5
	v_exp_f32_e32 v6, v6
	v_exp_f32_e32 v7, v7
	v_exp_f32_e32 v8, v8
	v_exp_f32_e32 v13, v9
	v_sub_f32_e32 v9, v60, v172
	v_exp_f32_e32 v14, v9
	v_sub_f32_e32 v9, v61, v172
	v_exp_f32_e32 v15, v9
	v_sub_f32_e32 v9, v62, v172
	v_cvt_pk_bf16_f32 v2, v0, v2
	v_lshl_add_u32 v0, s36, 14, v79
	v_exp_f32_e32 v48, v9
	v_sub_f32_e32 v9, v63, v172
	v_add_u32_e32 v50, v0, v76
	v_exp_f32_e32 v49, v9
	v_cvt_pk_bf16_f32 v3, v3, v4
	v_cvt_pk_bf16_f32 v4, v5, v6
	v_cvt_pk_bf16_f32 v5, v7, v8
	ds_read_b64_tr_b16 v[6:7], v50 offset:32768
	ds_read_b64_tr_b16 v[8:9], v50 offset:33792
	v_add_u32_e32 v0, v0, v77
	s_setprio 1
	s_waitcnt lgkmcnt(0)
	v_mfma_f32_32x32x16_bf16 v[16:31], v[2:5], v[6:9], v[16:31]
	ds_read_b64_tr_b16 v[6:7], v0 offset:32768
	ds_read_b64_tr_b16 v[8:9], v0 offset:33792
	s_mov_b32 s77, s76
	s_mov_b32 s78, s76
	s_mov_b32 s79, s76
	s_waitcnt lgkmcnt(0)
	v_mfma_f32_32x32x16_bf16 v[32:47], v[2:5], v[6:9], v[32:47]
	v_mov_b64_e32 v[6:7], s[76:77]
	v_mov_b64_e32 v[8:9], s[78:79]
	s_nop 1
	v_mfma_f32_32x32x16_bf16 v[80:95], v[2:5], v[6:9], v[80:95]
	v_cvt_pk_bf16_f32 v2, v10, v11
	v_cvt_pk_bf16_f32 v3, v12, v13
	v_cvt_pk_bf16_f32 v4, v14, v15
	v_cvt_pk_bf16_f32 v5, v48, v49
	ds_read_b64_tr_b16 v[10:11], v50 offset:34816
	ds_read_b64_tr_b16 v[12:13], v50 offset:35840
	s_waitcnt lgkmcnt(0)
	v_mfma_f32_32x32x16_bf16 v[16:31], v[2:5], v[10:13], v[16:31]
	ds_read_b64_tr_b16 v[10:11], v0 offset:34816
	ds_read_b64_tr_b16 v[12:13], v0 offset:35840
	s_waitcnt lgkmcnt(0)
	v_mfma_f32_32x32x16_bf16 v[32:47], v[2:5], v[10:13], v[32:47]
	v_mfma_f32_32x32x16_bf16 v[80:95], v[2:5], v[6:9], v[80:95]
	s_setprio 0
	s_movk_i32 s77, 0x110
	s_mov_b64 s[78:79], -1
	s_and_b64 vcc, exec, s[90:91]
	s_cbranch_vccz .LBB0_248

.LBB0_266:
	v_sub_f32_e32 v11, v11, v174
	v_sub_f32_e32 v10, v10, v174
	v_sub_f32_e32 v13, v13, v174
	v_sub_f32_e32 v12, v12, v174
	v_exp_f32_e32 v11, v11
	v_exp_f32_e32 v10, v10
	v_sub_f32_e32 v173, v173, v174
	v_sub_f32_e32 v145, v145, v174
	v_sub_f32_e32 v15, v15, v174
	v_sub_f32_e32 v14, v14, v174
	v_exp_f32_e32 v13, v13
	v_exp_f32_e32 v12, v12
	v_sub_f32_e32 v4, v4, v174
	v_exp_f32_e32 v173, v173
	v_exp_f32_e32 v145, v145
	v_exp_f32_e32 v15, v15
	v_exp_f32_e32 v14, v14
	v_sub_f32_e32 v8, v8, v174
	v_sub_f32_e32 v6, v6, v174
	v_exp_f32_e32 v180, v4
	v_sub_f32_e32 v3, v3, v174
	v_sub_f32_e32 v2, v2, v174
	s_lshl_b32 s17, s83, 14
	v_lshlrev_b32_e32 v4, 3, v144
	v_sub_f32_e32 v9, v9, v174
	v_exp_f32_e32 v176, v8
	v_sub_f32_e32 v7, v7, v174
	v_exp_f32_e32 v178, v6
	v_sub_f32_e32 v5, v5, v174
	v_exp_f32_e32 v181, v3
	v_exp_f32_e32 v174, v2
	s_add_i32 s17, s17, 0
	v_lshlrev_b32_e32 v2, 1, v164
	v_lshrrev_b32_e32 v3, 1, v165
	v_and_b32_e32 v6, 8, v4
	v_lshlrev_b32_e32 v8, 7, v162
	v_exp_f32_e32 v177, v7
	v_exp_f32_e32 v179, v5
	v_bitop3_b32 v7, v2, v162, v3 bitop3:0x36
	v_cvt_pk_bf16_f32 v5, v11, v10
	v_add3_u32 v10, s17, v6, v8
	v_cvt_pk_bf16_f32 v4, v13, v12
	v_lshl_add_u32 v12, v7, 4, v10
	v_exp_f32_e32 v175, v9
	v_or_b32_e32 v182, v2, v3
	v_cvt_pk_bf16_f32 v2, v173, v145
	v_cvt_pk_bf16_f32 v3, v15, v14
	ds_read_b64_tr_b16 v[6:7], v12 offset:32768
	ds_read_b64_tr_b16 v[8:9], v12 offset:33792
	s_setprio 1
	s_waitcnt lgkmcnt(0)
	v_mfma_f32_32x32x16_bf16 v[48:63], v[2:5], v[6:9], v[48:63]
	v_bitop3_b32 v6, v182, v162, 4 bitop3:0x36
	v_lshl_add_u32 v14, v6, 4, v10
	ds_read_b64_tr_b16 v[6:7], v14 offset:32768
	ds_read_b64_tr_b16 v[8:9], v14 offset:33792
	s_mov_b32 s77, s76
	s_mov_b32 s78, s76
	s_mov_b32 s79, s76
	ds_read_b64_tr_b16 v[10:11], v12 offset:34816
	ds_read_b64_tr_b16 v[12:13], v12 offset:35840
	s_waitcnt lgkmcnt(2)
	v_mfma_f32_32x32x16_bf16 v[64:79], v[2:5], v[6:9], v[64:79]
	v_mov_b64_e32 v[6:7], s[76:77]
	v_mov_b64_e32 v[8:9], s[78:79]
	s_movk_i32 s77, 0x110
	s_nop 0
	v_mfma_f32_32x32x16_bf16 v[112:127], v[2:5], v[6:9], v[112:127]
	v_cvt_pk_bf16_f32 v2, v175, v176
	v_cvt_pk_bf16_f32 v3, v177, v178
	v_cvt_pk_bf16_f32 v4, v179, v180
	v_cvt_pk_bf16_f32 v5, v181, v174
	s_waitcnt lgkmcnt(0)
	s_nop 0
	v_mfma_f32_32x32x16_bf16 v[48:63], v[2:5], v[10:13], v[48:63]
	ds_read_b64_tr_b16 v[10:11], v14 offset:34816
	ds_read_b64_tr_b16 v[12:13], v14 offset:35840
	s_waitcnt lgkmcnt(0)
	v_mfma_f32_32x32x16_bf16 v[64:79], v[2:5], v[10:13], v[64:79]
	v_mfma_f32_32x32x16_bf16 v[112:127], v[2:5], v[6:9], v[112:127]
	s_setprio 0

.LBB0_268:
	s_lshl_b32 s17, s83, 13
	s_or_b32 s40, s83, s95
	s_add_i32 s36, s17, 0
	s_lshl_b32 s40, s40, 8
	v_add_u32_e32 v10, s36, v167
	s_add_i32 s40, s40, 0
	s_add_i32 s40, s40, 0x18000
	v_add_u32_e32 v2, v10, v168
	v_add_u32_e32 v6, s40, v166
	ds_read_b128 v[2:5], v2 offset:4096
	ds_read_b128 v[48:51], v6 offset:128
	ds_read_b128 v[52:55], v6 offset:160
	ds_read_b128 v[56:59], v6 offset:192
	ds_read_b128 v[60:63], v6 offset:224
	v_add_u32_e32 v6, v10, v171
	s_setprio 1
	s_waitcnt lgkmcnt(0)
	v_mfma_f32_32x32x16_bf16 v[48:63], v[2:5], v[140:143], v[48:63]
	ds_read_b128 v[2:5], v6 offset:4096
	v_add_u32_e32 v6, v10, v169
	ds_read_b128 v[6:9], v6 offset:4096
	v_max_f32_e32 v11, v96, v96
	s_waitcnt lgkmcnt(1)
	v_mfma_f32_32x32x16_bf16 v[48:63], v[2:5], v[136:139], v[48:63]
	v_add_u32_e32 v2, v10, v170
	ds_read_b128 v[2:5], v2 offset:4096
	v_max_f32_e32 v10, v97, v97
	v_max_f32_e32 v10, v11, v10
	v_max3_f32 v10, v10, v98, v99
	v_max3_f32 v10, v10, v100, v101
	s_waitcnt lgkmcnt(1)
	v_mfma_f32_32x32x16_bf16 v[48:63], v[6:9], v[132:135], v[48:63]
	v_max3_f32 v6, v10, v102, v103
	v_max3_f32 v6, v6, v104, v105
	v_max3_f32 v6, v6, v106, v107
	v_max3_f32 v6, v6, v108, v109
	v_max3_f32 v6, v6, v110, v111
	ds_bpermute_b32 v7, v147, v6
	s_waitcnt lgkmcnt(1)
	v_mfma_f32_32x32x16_bf16 v[48:63], v[2:5], v[128:131], v[48:63]
	s_setprio 0
	s_waitcnt lgkmcnt(0)
	v_max_f32_e32 v2, v7, v7
	v_max_f32_e32 v2, v6, v2
	v_cmp_ge_f32_e32 vcc, v2, v161
	s_cbranch_vccz .LBB0_273
	v_add_f32_e32 v3, 0x41000000, v172
	v_cmp_gt_f32_e32 vcc, v2, v3
	s_cbranch_vccz .LBB0_274
	v_max_f32_e32 v2, v2, v2
	v_max_f32_e32 v3, v172, v172
	v_max_f32_e32 v2, v3, v2
	v_cmp_gt_u32_e32 vcc, 32, v144
	s_and_saveexec_b64 s[78:79], vcc
	s_cbranch_execz .LBB0_272
	v_sub_f32_e32 v3, v172, v2
	v_exp_f32_e32 v3, v3
	v_readlane_b32 s40, v251, 13
	s_nop 1
	v_lshl_add_u32 v4, v149, 2, s40
	ds_write_b32 v4, v3

.LBB0_275:
	v_sub_f32_e32 v11, v104, v2
	v_exp_f32_e32 v12, v11
	v_sub_f32_e32 v11, v105, v2
	v_exp_f32_e32 v13, v11
	v_sub_f32_e32 v11, v106, v2
	v_sub_f32_e32 v3, v96, v2
	v_sub_f32_e32 v4, v97, v2
	v_exp_f32_e32 v14, v11
	v_sub_f32_e32 v11, v107, v2
	v_exp_f32_e32 v3, v3
	v_exp_f32_e32 v4, v4
	v_exp_f32_e32 v15, v11
	v_sub_f32_e32 v11, v108, v2
	v_exp_f32_e32 v64, v11
	v_sub_f32_e32 v11, v109, v2
	v_sub_f32_e32 v5, v98, v2
	v_sub_f32_e32 v6, v99, v2
	v_sub_f32_e32 v7, v100, v2
	v_sub_f32_e32 v8, v101, v2
	v_sub_f32_e32 v9, v102, v2
	v_sub_f32_e32 v10, v103, v2
	v_exp_f32_e32 v65, v11
	v_sub_f32_e32 v11, v110, v2
	v_exp_f32_e32 v5, v5
	v_exp_f32_e32 v6, v6
	v_exp_f32_e32 v7, v7
	v_exp_f32_e32 v8, v8
	v_exp_f32_e32 v9, v9
	v_exp_f32_e32 v10, v10
	v_exp_f32_e32 v66, v11
	v_sub_f32_e32 v11, v111, v2
	s_lshl_b32 s40, s83, 14
	v_lshlrev_b32_e32 v70, 3, v144
	v_exp_f32_e32 v67, v11
	s_add_i32 s40, s40, 0
	v_lshlrev_b32_e32 v11, 1, v164
	v_lshrrev_b32_e32 v68, 1, v165
	v_and_b32_e32 v70, 8, v70
	v_cvt_pk_bf16_f32 v4, v3, v4
	v_lshlrev_b32_e32 v3, 7, v162
	v_or_b32_e32 v69, v11, v68
	v_bitop3_b32 v11, v11, v162, v68 bitop3:0x36
	v_add3_u32 v3, s40, v70, v3
	v_lshl_add_u32 v68, v11, 4, v3
	v_cvt_pk_bf16_f32 v5, v5, v6
	v_cvt_pk_bf16_f32 v6, v7, v8
	v_cvt_pk_bf16_f32 v7, v9, v10
	ds_read_b64_tr_b16 v[8:9], v68 offset:32768
	ds_read_b64_tr_b16 v[10:11], v68 offset:33792
	s_setprio 1
	s_waitcnt lgkmcnt(0)
	v_mfma_f32_32x32x16_bf16 v[16:31], v[4:7], v[8:11], v[16:31]
	v_bitop3_b32 v8, v69, v162, 4 bitop3:0x36
	v_lshl_add_u32 v3, v8, 4, v3
	ds_read_b64_tr_b16 v[8:9], v3 offset:32768
	ds_read_b64_tr_b16 v[10:11], v3 offset:33792
	s_mov_b32 s77, s76
	s_mov_b32 s78, s76
	s_mov_b32 s79, s76
	s_waitcnt lgkmcnt(0)
	v_mfma_f32_32x32x16_bf16 v[32:47], v[4:7], v[8:11], v[32:47]
	v_mov_b64_e32 v[8:9], s[76:77]
	v_mov_b64_e32 v[10:11], s[78:79]
	s_movk_i32 s77, 0x110
	s_nop 0
	v_mfma_f32_32x32x16_bf16 v[80:95], v[4:7], v[8:11], v[80:95]
	v_cvt_pk_bf16_f32 v4, v12, v13
	v_cvt_pk_bf16_f32 v5, v14, v15
	v_cvt_pk_bf16_f32 v6, v64, v65
	v_cvt_pk_bf16_f32 v7, v66, v67
	ds_read_b64_tr_b16 v[12:13], v68 offset:34816
	ds_read_b64_tr_b16 v[14:15], v68 offset:35840
	s_waitcnt lgkmcnt(0)
	v_mfma_f32_32x32x16_bf16 v[16:31], v[4:7], v[12:15], v[16:31]
	ds_read_b64_tr_b16 v[12:13], v3 offset:34816
	ds_read_b64_tr_b16 v[14:15], v3 offset:35840
	s_waitcnt lgkmcnt(0)
	v_mfma_f32_32x32x16_bf16 v[32:47], v[4:7], v[12:15], v[32:47]
	v_mfma_f32_32x32x16_bf16 v[80:95], v[4:7], v[8:11], v[80:95]
	s_setprio 0

.LBB0_282:
	v_sub_f32_e32 v12, v12, v50
	v_sub_f32_e32 v11, v11, v50
	v_exp_f32_e32 v12, v12
	v_exp_f32_e32 v11, v11
	v_sub_f32_e32 v5, v5, v50
	v_sub_f32_e32 v2, v64, v50
	v_sub_f32_e32 v49, v49, v50
	v_sub_f32_e32 v48, v48, v50
	v_sub_f32_e32 v15, v15, v50
	v_sub_f32_e32 v14, v14, v50
	v_sub_f32_e32 v13, v13, v50
	v_exp_f32_e32 v55, v5
	v_lshlrev_b32_e32 v5, 3, v144
	v_exp_f32_e32 v2, v2
	v_exp_f32_e32 v49, v49
	v_exp_f32_e32 v48, v48
	v_exp_f32_e32 v15, v15
	v_exp_f32_e32 v14, v14
	v_exp_f32_e32 v13, v13
	v_sub_f32_e32 v7, v7, v50
	v_sub_f32_e32 v6, v6, v50
	v_sub_f32_e32 v4, v4, v50
	v_sub_f32_e32 v3, v3, v50
	s_add_i32 s36, s36, s17
	v_and_b32_e32 v5, 8, v5
	v_sub_f32_e32 v10, v10, v50
	v_sub_f32_e32 v9, v9, v50
	v_sub_f32_e32 v8, v8, v50
	v_exp_f32_e32 v53, v7
	v_exp_f32_e32 v54, v6
	v_exp_f32_e32 v56, v4
	v_exp_f32_e32 v50, v3
	v_add_lshl_u32 v6, v146, v163, 7
	v_lshlrev_b32_e32 v3, 1, v164
	v_lshrrev_b32_e32 v4, 1, v165
	v_add_u32_e32 v7, s36, v5
	v_exp_f32_e32 v52, v8
	v_bitop3_b32 v8, v3, v162, v4 bitop3:0x36
	v_cvt_pk_bf16_f32 v5, v12, v11
	v_add3_u32 v11, v6, v7, s21
	v_lshl_add_u32 v12, v8, 4, v11
	v_exp_f32_e32 v51, v9
	v_or_b32_e32 v57, v3, v4
	v_cvt_pk_bf16_f32 v2, v2, v49
	v_cvt_pk_bf16_f32 v3, v48, v15
	v_cvt_pk_bf16_f32 v4, v14, v13
	ds_read_b64_tr_b16 v[6:7], v12 offset:32768
	ds_read_b64_tr_b16 v[8:9], v12 offset:33792
	s_setprio 1
	s_waitcnt lgkmcnt(0)
	v_mfma_f32_32x32x16_bf16 v[16:31], v[2:5], v[6:9], v[16:31]
	v_bitop3_b32 v6, v57, v162, 4 bitop3:0x36
	v_lshl_add_u32 v14, v6, 4, v11
	ds_read_b64_tr_b16 v[6:7], v14 offset:32768
	ds_read_b64_tr_b16 v[8:9], v14 offset:33792
	v_exp_f32_e32 v10, v10
	s_mov_b32 s77, s76
	s_mov_b32 s78, s76
	s_mov_b32 s79, s76
	s_waitcnt lgkmcnt(0)
	v_mfma_f32_32x32x16_bf16 v[32:47], v[2:5], v[6:9], v[32:47]
	v_mov_b64_e32 v[6:7], s[76:77]
	v_mov_b64_e32 v[8:9], s[78:79]
	s_movk_i32 s77, 0x110
	s_nop 0
	v_mfma_f32_32x32x16_bf16 v[80:95], v[2:5], v[6:9], v[80:95]
	v_cvt_pk_bf16_f32 v2, v10, v51
	v_cvt_pk_bf16_f32 v3, v52, v53
	v_cvt_pk_bf16_f32 v4, v54, v55
	v_cvt_pk_bf16_f32 v5, v56, v50
	ds_read_b64_tr_b16 v[10:11], v12 offset:34816
	ds_read_b64_tr_b16 v[12:13], v12 offset:35840
	s_waitcnt lgkmcnt(0)
	v_mfma_f32_32x32x16_bf16 v[16:31], v[2:5], v[10:13], v[16:31]
	ds_read_b64_tr_b16 v[10:11], v14 offset:34816
	ds_read_b64_tr_b16 v[12:13], v14 offset:35840
	s_waitcnt lgkmcnt(0)
	v_mfma_f32_32x32x16_bf16 v[32:47], v[2:5], v[10:13], v[32:47]
	v_mfma_f32_32x32x16_bf16 v[80:95], v[2:5], v[6:9], v[80:95]
	s_setprio 0

.LBB0_292:
	s_nop 1
	v_rcp_f32_e32 v2, v112
	v_rcp_f32_e32 v4, v114
	v_readlane_b32 s1, v251, 15
	v_rcp_f32_e32 v3, v113
	v_mul_f32_e32 v6, v48, v2
	v_mul_f32_e32 v7, v64, v2
	v_rcp_f32_e32 v2, v115
	v_mul_f32_e32 v9, v50, v4
	v_mul_f32_e32 v10, v66, v4
	v_rcp_f32_e32 v4, v116
	v_mul_f32_e32 v11, v51, v2
	v_mul_f32_e32 v12, v67, v2
	v_rcp_f32_e32 v2, v117
	v_mul_f32_e32 v13, v52, v4
	v_mul_f32_e32 v14, v68, v4
	v_rcp_f32_e32 v4, v118
	v_mul_f32_e32 v15, v53, v2
	v_mul_f32_e32 v16, v69, v2
	v_rcp_f32_e32 v2, v119
	v_mul_f32_e32 v17, v54, v4
	v_mul_f32_e32 v18, v70, v4
	v_rcp_f32_e32 v4, v120
	v_mul_f32_e32 v19, v55, v2
	v_mul_f32_e32 v20, v71, v2
	v_rcp_f32_e32 v2, v121
	v_mul_f32_e32 v21, v56, v4
	v_mul_f32_e32 v22, v72, v4
	v_rcp_f32_e32 v4, v122
	v_mul_f32_e32 v23, v57, v2
	v_mul_f32_e32 v24, v73, v2
	v_rcp_f32_e32 v2, v123
	v_mul_f32_e32 v25, v58, v4
	v_mul_f32_e32 v26, v74, v4
	v_rcp_f32_e32 v4, v124
	v_mul_f32_e32 v27, v59, v2
	v_mul_f32_e32 v28, v75, v2
	v_rcp_f32_e32 v2, v125
	v_mul_f32_e32 v29, v60, v4
	v_mul_f32_e32 v30, v76, v4
	v_rcp_f32_e32 v4, v126
	v_mul_f32_e32 v31, v61, v2
	v_mul_f32_e32 v32, v77, v2
	v_mov_b32_e32 v2, s1
	v_rcp_f32_e32 v5, v127
	v_mul_f32_e32 v8, v49, v3
	v_add_u32_e32 v37, 0, v2
	v_lshlrev_b32_e32 v2, 1, v144
	v_and_b32_e32 v2, 62, v2
	v_mul_f32_e32 v3, v65, v3
	v_mul_f32_e32 v33, v62, v4
	v_mul_f32_e32 v34, v78, v4
	v_and_b32_e32 v4, 0xffffffc, v148
	v_add_u32_e32 v2, v37, v2
	s_movk_i32 s36, 0x90
	v_mul_f32_e32 v35, v63, v5
	v_mul_f32_e32 v36, v79, v5
	v_mad_u64_u32 v[4:5], s[42:43], v4, s36, v[2:3]
	v_cvt_pk_bf16_f32 v3, v3, s0
	ds_write_b16 v4, v3 offset:208
	v_cvt_pk_bf16_f32 v3, v9, s0
	ds_write_b16 v4, v3 offset:288
	v_cvt_pk_bf16_f32 v3, v10, s0
	v_cvt_pk_bf16_f32 v5, v6, s0
	ds_write_b16 v4, v3 offset:352
	v_or_b32_e32 v3, 3, v148
	ds_write_b16 v4, v5
	v_cvt_pk_bf16_f32 v5, v7, s0
	v_mad_u64_u32 v[2:3], s[42:43], v3, s36, v[2:3]
	ds_write_b16 v4, v5 offset:64
	v_cvt_pk_bf16_f32 v5, v8, s0
	v_cvt_pk_bf16_f32 v3, v11, s0
	ds_write_b16 v4, v5 offset:144
	ds_write_b16 v2, v3
	v_cvt_pk_bf16_f32 v3, v12, s0
	ds_write_b16 v2, v3 offset:64
	v_cvt_pk_bf16_f32 v3, v13, s0
	ds_write_b16 v4, v3 offset:1152
	v_cvt_pk_bf16_f32 v3, v14, s0
	ds_write_b16 v4, v3 offset:1216
	v_cvt_pk_bf16_f32 v3, v15, s0
	ds_write_b16 v4, v3 offset:1296
	v_cvt_pk_bf16_f32 v3, v16, s0
	ds_write_b16 v4, v3 offset:1360
	v_cvt_pk_bf16_f32 v3, v17, s0
	ds_write_b16 v4, v3 offset:1440
	v_cvt_pk_bf16_f32 v3, v18, s0
	ds_write_b16 v4, v3 offset:1504
	v_cvt_pk_bf16_f32 v3, v19, s0
	ds_write_b16 v2, v3 offset:1152
	v_cvt_pk_bf16_f32 v3, v20, s0
	ds_write_b16 v2, v3 offset:1216
	v_cvt_pk_bf16_f32 v3, v21, s0
	ds_write_b16 v4, v3 offset:2304
	v_cvt_pk_bf16_f32 v3, v22, s0
	ds_write_b16 v4, v3 offset:2368
	v_cvt_pk_bf16_f32 v3, v23, s0
	ds_write_b16 v4, v3 offset:2448
	v_cvt_pk_bf16_f32 v3, v24, s0
	ds_write_b16 v4, v3 offset:2512
	v_cvt_pk_bf16_f32 v3, v25, s0
	ds_write_b16 v4, v3 offset:2592
	v_cvt_pk_bf16_f32 v3, v26, s0
	ds_write_b16 v4, v3 offset:2656
	v_cvt_pk_bf16_f32 v3, v27, s0
	ds_write_b16 v2, v3 offset:2304
	v_cvt_pk_bf16_f32 v3, v28, s0
	ds_write_b16 v2, v3 offset:2368
	v_cvt_pk_bf16_f32 v3, v29, s0
	ds_write_b16 v4, v3 offset:3456
	v_cvt_pk_bf16_f32 v3, v30, s0
	s_lshl_b32 s1, s11, 12
	ds_write_b16 v4, v3 offset:3520
	v_cvt_pk_bf16_f32 v3, v31, s0
	s_add_i32 s42, s82, s1
	ds_write_b16 v4, v3 offset:3600
	v_cvt_pk_bf16_f32 v3, v32, s0
	s_ashr_i32 s43, s42, 31
	ds_write_b16 v4, v3 offset:3664
	v_cvt_pk_bf16_f32 v3, v33, s0
	s_lshl_b64 s[42:43], s[42:43], 11
	v_readlane_b32 s11, v255, 54
	ds_write_b16 v4, v3 offset:3744
	v_cvt_pk_bf16_f32 v3, v34, s0
	s_add_u32 s11, s11, s42
	v_readlane_b32 s17, v255, 55
	ds_write_b16 v4, v3 offset:3808
	v_cvt_pk_bf16_f32 v3, v35, s0
	s_addc_u32 s17, s17, s43
	ds_write_b16 v2, v3 offset:3456
	v_cvt_pk_bf16_f32 v3, v36, s0
	s_add_u32 s42, s11, s16
	ds_write_b16 v2, v3 offset:3520
	s_addc_u32 s43, s17, 0
	v_lshlrev_b32_e32 v0, 4, v0
	v_mul_lo_u32 v2, v148, s36
	s_waitcnt lgkmcnt(0)
	v_lshl_add_u64 v[6:7], s[42:43], 0, v[0:1]
	v_add3_u32 v0, v37, v0, v2
	ds_read_b128 v[2:5], v0
	v_ashrrev_i32_e32 v149, 31, v148
	v_lshlrev_b64 v[8:9], 11, v[148:149]
	v_lshl_add_u64 v[10:11], v[6:7], 0, v[8:9]
	ds_read_b128 v[6:9], v0 offset:1152
	s_waitcnt lgkmcnt(1)
	global_store_dwordx4 v[10:11], v[2:5], off
	s_lshl_b32 s11, s10, 8
	v_readlane_b32 s17, v251, 7
	v_add_co_u32_e32 v2, vcc, s14, v10
	s_add_i32 s82, s11, s17
	s_nop 0
	v_addc_co_u32_e32 v3, vcc, 0, v11, vcc
	s_waitcnt lgkmcnt(0)
	global_store_dwordx4 v[2:3], v[6:9], off
	ds_read_b128 v[2:5], v0 offset:2304
	ds_read_b128 v[6:9], v0 offset:3456
	v_add_co_u32_e32 v12, vcc, s81, v10
	s_mul_i32 s36, s82, 0x1400
	s_nop 0
	v_addc_co_u32_e32 v13, vcc, 0, v11, vcc
	s_waitcnt lgkmcnt(1)
	global_store_dwordx4 v[12:13], v[2:5], off
	v_mov_b32_e32 v144, v226
	v_mov_b32_e32 v0, v227
	v_add_co_u32_e32 v2, vcc, s18, v10
	s_mov_b32 s83, s37
	s_nop 0
	v_addc_co_u32_e32 v3, vcc, 0, v11, vcc
	s_mul_hi_u32 s17, s82, 0x1400
	s_add_u32 s42, s84, s36
	s_waitcnt lgkmcnt(0)
	global_store_dwordx4 v[2:3], v[6:9], off
	s_addc_u32 s43, s85, s17
	v_and_b32_e32 v161, 31, v144
	v_ashrrev_i32_e32 v18, 5, v144
	s_lshl_b64 s[44:45], s[82:83], 2
	v_mul_u32_u24_e32 v0, 0xa00, v161
	v_lshlrev_b32_e32 v148, 2, v18
	s_add_u32 s44, s28, s44
	v_lshl_add_u32 v0, v18, 3, v0
	s_addc_u32 s45, s29, s45
	v_ashrrev_i32_e32 v149, 31, v148
	v_lshl_add_u64 v[2:3], v[0:1], 1, s[42:43]
	v_lshl_add_u64 v[14:15], v[148:149], 2, s[44:45]
	global_load_dwordx4 v[128:131], v[2:3], off offset:2048
	global_load_dwordx4 v[20:23], v[2:3], off offset:3072
	s_nop 0
	global_load_dwordx4 v[2:5], v[14:15], off
	global_load_dwordx4 v[6:9], v[14:15], off offset:32
	global_load_dwordx4 v[10:13], v[14:15], off offset:64
	s_nop 0
	global_load_dwordx4 v[14:17], v[14:15], off offset:96
	v_add_u32_e32 v24, 16, v0
	v_mov_b32_e32 v25, v1
	v_lshl_add_u64 v[28:29], v[24:25], 1, s[42:43]
	global_load_dwordx4 v[24:27], v[28:29], off offset:3072
	global_load_dwordx4 v[140:143], v[28:29], off offset:2048
	s_setprio 1
	s_waitcnt vmcnt(2)
	v_mfma_f32_32x32x16_bf16 v[2:17], v[20:23], v[128:131], v[2:17]
	v_add_u32_e32 v20, 32, v0
	v_mov_b32_e32 v21, v1
	v_lshl_add_u64 v[28:29], v[20:21], 1, s[42:43]
	global_load_dwordx4 v[20:23], v[28:29], off offset:3072
	global_load_dwordx4 v[136:139], v[28:29], off offset:2048
	v_add_u32_e32 v0, 48, v0
	v_lshl_add_u64 v[28:29], v[0:1], 1, s[42:43]
	s_waitcnt vmcnt(2)
	v_mfma_f32_32x32x16_bf16 v[2:17], v[24:27], v[140:143], v[2:17]
	global_load_dwordx4 v[24:27], v[28:29], off offset:3072
	global_load_dwordx4 v[132:135], v[28:29], off offset:2048
	v_cmp_gt_i32_e64 s[42:43], v148, v161
	v_cmp_lt_i32_e64 s[44:45], v148, v161
	v_cmp_eq_u32_e32 vcc, 0, v144
	s_waitcnt vmcnt(2)
	v_mfma_f32_32x32x16_bf16 v[2:17], v[20:23], v[136:139], v[2:17]
	s_waitcnt vmcnt(0)
	v_mfma_f32_32x32x16_bf16 v[2:17], v[24:27], v[132:135], v[2:17]
	s_setprio 0
	s_nop 11
	v_max_f32_e32 v0, v2, v2
	v_max_f32_e32 v0, 0xff800000, v0
	v_cndmask_b32_e64 v0, v0, v220, s[42:43]
	v_max_f32_e32 v2, v3, v3
	v_max_f32_e32 v2, v0, v2
	v_cndmask_b32_e64 v0, v0, v2, s[44:45]
	v_or_b32_e32 v2, 2, v148
	v_max_f32_e32 v3, v4, v4
	v_max_f32_e32 v3, v0, v3
	v_cmp_gt_i32_e64 s[46:47], v2, v161
	v_or_b32_e32 v2, 3, v148
	v_cmp_gt_i32_e64 s[48:49], v2, v161
	v_cndmask_b32_e64 v0, v3, v0, s[46:47]
	v_max_f32_e32 v3, v5, v5
	v_max_f32_e32 v3, v0, v3
	v_cndmask_b32_e64 v0, v3, v0, s[48:49]
	v_add_u32_e32 v2, 8, v148
	v_max_f32_e32 v3, v6, v6
	v_max_f32_e32 v3, v0, v3
	v_cmp_gt_i32_e64 s[50:51], v2, v161
	v_add_u32_e32 v2, 9, v148
	v_max_f32_e32 v4, v7, v7
	v_cndmask_b32_e64 v0, v3, v0, s[50:51]
	v_max_f32_e32 v3, v0, v0
	v_max_f32_e32 v3, v3, v4
	v_cmp_gt_i32_e64 s[52:53], v2, v161
	v_add_u32_e32 v2, 10, v148
	v_max_f32_e32 v4, v8, v8
	v_cndmask_b32_e64 v0, v3, v0, s[52:53]
	v_max_f32_e32 v3, v0, v0
	v_max_f32_e32 v3, v3, v4
	v_cmp_gt_i32_e64 s[54:55], v2, v161
	v_add_u32_e32 v2, 11, v148
	v_max_f32_e32 v4, v9, v9
	v_cndmask_b32_e64 v0, v3, v0, s[54:55]
	v_max_f32_e32 v3, v0, v0
	v_max_f32_e32 v3, v3, v4
	v_cmp_gt_i32_e64 s[56:57], v2, v161
	v_add_u32_e32 v2, 16, v148
	v_max_f32_e32 v4, v10, v10
	v_cndmask_b32_e64 v0, v3, v0, s[56:57]
	v_max_f32_e32 v3, v0, v0
	v_max_f32_e32 v3, v3, v4
	v_cmp_gt_i32_e64 s[58:59], v2, v161
	v_add_u32_e32 v2, 17, v148
	v_max_f32_e32 v4, v11, v11
	v_cndmask_b32_e64 v0, v3, v0, s[58:59]
	v_max_f32_e32 v3, v0, v0
	v_max_f32_e32 v3, v3, v4
	v_cmp_gt_i32_e64 s[60:61], v2, v161
	v_add_u32_e32 v2, 18, v148
	v_max_f32_e32 v4, v12, v12
	v_cndmask_b32_e64 v0, v3, v0, s[60:61]
	v_max_f32_e32 v3, v0, v0
	v_max_f32_e32 v3, v3, v4
	v_cmp_gt_i32_e64 s[62:63], v2, v161
	v_add_u32_e32 v2, 19, v148
	v_max_f32_e32 v4, v13, v13
	v_cndmask_b32_e64 v0, v3, v0, s[62:63]
	v_max_f32_e32 v3, v0, v0
	v_max_f32_e32 v3, v3, v4
	v_cmp_gt_i32_e64 s[64:65], v2, v161
	v_add_u32_e32 v2, 24, v148
	v_max_f32_e32 v4, v14, v14
	v_cndmask_b32_e64 v0, v3, v0, s[64:65]
	v_max_f32_e32 v3, v0, v0
	v_max_f32_e32 v3, v3, v4
	v_cmp_gt_i32_e64 s[66:67], v2, v161
	v_add_u32_e32 v2, 25, v148
	v_max_f32_e32 v4, v15, v15
	v_cndmask_b32_e64 v0, v3, v0, s[66:67]
	v_max_f32_e32 v3, v0, v0
	v_max_f32_e32 v3, v3, v4
	v_cmp_gt_i32_e64 s[68:69], v2, v161
	v_add_u32_e32 v2, 26, v148
	v_max_f32_e32 v5, v16, v16
	v_cndmask_b32_e64 v0, v3, v0, s[68:69]
	global_load_dword v3, v1, s[96:97]
	v_max_f32_e32 v4, v0, v0
	v_max_f32_e32 v4, v4, v5
	v_cmp_gt_i32_e64 s[70:71], v2, v161
	v_max_f32_e32 v5, v17, v17
	v_and_b32_e32 v6, 0xffff0000, v128
	v_cndmask_b32_e64 v0, v4, v0, s[70:71]
	v_max_f32_e32 v4, v0, v0
	v_max_f32_e32 v4, v4, v5
	v_lshlrev_b32_e32 v5, 16, v128
	v_mul_f32_e32 v6, v6, v6
	v_fmac_f32_e32 v6, v5, v5
	v_lshlrev_b32_e32 v5, 16, v129
	v_fmac_f32_e32 v6, v5, v5
	v_and_b32_e32 v5, 0xffff0000, v129
	v_fmac_f32_e32 v6, v5, v5
	v_lshlrev_b32_e32 v5, 16, v130
	v_fmac_f32_e32 v6, v5, v5
	v_and_b32_e32 v5, 0xffff0000, v130
	v_fmac_f32_e32 v6, v5, v5
	v_lshlrev_b32_e32 v5, 16, v131
	v_fmac_f32_e32 v6, v5, v5
	v_and_b32_e32 v5, 0xffff0000, v131
	v_fmac_f32_e32 v6, v5, v5
	v_lshlrev_b32_e32 v5, 16, v140
	v_fmac_f32_e32 v6, v5, v5
	v_and_b32_e32 v5, 0xffff0000, v140
	v_fmac_f32_e32 v6, v5, v5
	v_lshlrev_b32_e32 v5, 16, v141
	v_fmac_f32_e32 v6, v5, v5
	v_and_b32_e32 v5, 0xffff0000, v141
	v_fmac_f32_e32 v6, v5, v5
	v_lshlrev_b32_e32 v5, 16, v142
	v_fmac_f32_e32 v6, v5, v5
	v_and_b32_e32 v5, 0xffff0000, v142
	v_fmac_f32_e32 v6, v5, v5
	v_lshlrev_b32_e32 v5, 16, v143
	v_fmac_f32_e32 v6, v5, v5
	v_and_b32_e32 v5, 0xffff0000, v143
	v_fmac_f32_e32 v6, v5, v5
	v_lshlrev_b32_e32 v5, 16, v136
	v_fmac_f32_e32 v6, v5, v5
	v_and_b32_e32 v5, 0xffff0000, v136
	v_fmac_f32_e32 v6, v5, v5
	v_lshlrev_b32_e32 v5, 16, v137
	v_fmac_f32_e32 v6, v5, v5
	v_and_b32_e32 v5, 0xffff0000, v137
	v_fmac_f32_e32 v6, v5, v5
	v_lshlrev_b32_e32 v5, 16, v138
	v_fmac_f32_e32 v6, v5, v5
	v_and_b32_e32 v5, 0xffff0000, v138
	v_fmac_f32_e32 v6, v5, v5
	v_lshlrev_b32_e32 v5, 16, v139
	v_fmac_f32_e32 v6, v5, v5
	v_and_b32_e32 v5, 0xffff0000, v139
	v_fmac_f32_e32 v6, v5, v5
	v_lshlrev_b32_e32 v5, 16, v132
	v_fmac_f32_e32 v6, v5, v5
	v_and_b32_e32 v5, 0xffff0000, v132
	v_fmac_f32_e32 v6, v5, v5
	v_lshlrev_b32_e32 v5, 16, v133
	v_fmac_f32_e32 v6, v5, v5
	v_and_b32_e32 v5, 0xffff0000, v133
	v_fmac_f32_e32 v6, v5, v5
	v_lshlrev_b32_e32 v5, 16, v134
	v_fmac_f32_e32 v6, v5, v5
	v_and_b32_e32 v5, 0xffff0000, v134
	v_fmac_f32_e32 v6, v5, v5
	v_lshlrev_b32_e32 v5, 16, v135
	v_fmac_f32_e32 v6, v5, v5
	v_and_b32_e32 v5, 0xffff0000, v135
	v_fmac_f32_e32 v6, v5, v5
	v_add_u32_e32 v2, 27, v148
	ds_bpermute_b32 v5, v147, v6
	v_cmp_gt_i32_e64 s[72:73], v2, v161
	s_nop 1
	v_cndmask_b32_e64 v0, v4, v0, s[72:73]
	ds_bpermute_b32 v2, v147, v0
	s_waitcnt lgkmcnt(1)
	v_add_f32_e32 v4, v6, v5
	s_waitcnt vmcnt(0)
	v_mul_f32_e32 v3, v3, v4
	v_sqrt_f32_e32 v3, v3
	v_max_f32_e32 v0, v0, v0
	s_waitcnt lgkmcnt(0)
	v_max_f32_e32 v2, v2, v2
	v_max_f32_e32 v0, v0, v2
	v_add_f32_e32 v162, 0xc2200000, v0
	v_fmamk_f32 v0, v3, 0xbf8020c5, v162
	v_add_f32_e32 v0, 0xbc23d70a, v0
	ds_bpermute_b32 v2, v156, v0
	s_waitcnt lgkmcnt(0)
	v_max_f32_e32 v2, v2, v2
	v_min_f32_e32 v0, v0, v2
	ds_bpermute_b32 v2, v157, v0
	s_waitcnt lgkmcnt(0)
	v_max_f32_e32 v2, v2, v2
	v_min_f32_e32 v0, v0, v2
	ds_bpermute_b32 v2, v158, v0
	s_waitcnt lgkmcnt(0)
	v_max_f32_e32 v2, v2, v2
	v_min_f32_e32 v0, v0, v2
	ds_bpermute_b32 v2, v159, v0
	s_waitcnt lgkmcnt(0)
	v_max_f32_e32 v2, v2, v2
	v_min_f32_e32 v0, v0, v2
	ds_bpermute_b32 v2, v160, v0
	s_and_saveexec_b64 s[74:75], vcc
	s_cbranch_execz .LBB0_294
	s_waitcnt lgkmcnt(0)
	v_max_f32_e32 v2, v2, v2
	v_max_f32_e32 v0, v0, v0
	v_readlane_b32 s17, v251, 13
	v_min_f32_e32 v0, v0, v2
	s_nop 0
	v_mov_b32_e32 v2, s17
	ds_write_b32 v2, v0

.LBB0_296:
	s_or_b64 exec, exec, s[74:75]
	s_waitcnt lgkmcnt(6)
	v_max_f32_e32 v6, v6, v6
	v_max_f32_e32 v0, v0, v0
	v_min_f32_e32 v0, v0, v6
	s_waitcnt lgkmcnt(4)
	v_min3_f32 v0, v0, v2, v4
	s_waitcnt lgkmcnt(2)
	v_min3_f32 v0, v0, v5, v7
	s_waitcnt lgkmcnt(0)
	v_min3_f32 v2, v0, v8, v9
	v_ashrrev_i32_e32 v146, 3, v144
	v_readlane_b32 s17, v251, 12
	s_waitcnt vmcnt(0)
	v_cmp_ge_f32_e32 vcc, v3, v2
	s_lshl_b32 s10, s10, 2
	v_add_u32_e32 v0, s17, v146
	s_movk_i32 s17, 0xa00
	v_mul_lo_u32 v0, v0, s17
	s_ff1_i32_b64 s17, vcc
	s_min_u32 s10, s17, s10
	s_cmp_lg_u64 vcc, 0
	v_xor_b32_e32 v4, v146, v144
	s_cselect_b32 s96, s10, 0
	v_lshlrev_b32_e32 v4, 3, v4
	s_lshl_b32 s10, s96, 6
	s_mul_i32 s17, s96, 0x50000
	v_and_or_b32 v0, v4, 56, v0
	s_add_u32 s74, s84, s17
	s_addc_u32 s75, s85, 0
	v_lshlrev_b64 v[64:65], 1, v[0:1]
	s_waitcnt lgkmcnt(0)
	s_barrier
	v_lshl_add_u64 v[2:3], s[74:75], 0, v[64:65]
	s_mov_b64 s[78:79], 0xc00
	s_add_u32 s74, s30, s17
	v_lshl_add_u64 v[2:3], v[2:3], 0, s[78:79]
	s_mov_b32 s36, m0
	s_mov_b32 m0, s0
	s_nop 0
	global_load_lds_dwordx4 v[2:3], off
	s_mov_b32 m0, s36
	s_addc_u32 s75, s31, 0
	v_lshl_add_u64 v[2:3], s[74:75], 0, v[64:65]
	s_mov_b32 s36, m0
	s_mov_b32 m0, s27
	s_nop 0
	global_load_lds_dwordx4 v[2:3], off
	s_mov_b32 m0, s36
	s_lshl_b32 s36, s96, 8
	s_add_u32 s74, s28, s36
	v_ashrrev_i32_e32 v145, 31, v144
	s_addc_u32 s75, s29, 0
	v_lshlrev_b64 v[6:7], 2, v[144:145]
	v_lshl_add_u64 v[2:3], s[74:75], 0, v[6:7]
	s_mov_b32 s40, m0
	s_mov_b32 m0, s26
	s_nop 0
	global_load_lds_dword v[2:3], off
	s_mov_b32 m0, s40
	s_add_i32 s26, s10, 64
	s_add_i32 s40, s17, 0x50000
	s_mul_hi_u32 s26, s26, 0x1400
	s_add_u32 s74, s84, s40
	s_addc_u32 s75, s85, s26
	v_lshl_add_u64 v[4:5], s[74:75], 0, v[64:65]
	v_lshl_add_u64 v[4:5], v[4:5], 0, s[78:79]
	s_mov_b32 s74, m0
	s_mov_b32 m0, s23
	s_nop 0
	global_load_lds_dwordx4 v[4:5], off
	s_mov_b32 m0, s74
	s_add_u32 s74, s30, s40
	s_addc_u32 s75, s31, s26
	v_lshl_add_u64 v[4:5], s[74:75], 0, v[64:65]
	s_mov_b32 s23, m0
	s_mov_b32 m0, s22
	s_nop 0
	global_load_lds_dwordx4 v[4:5], off
	s_mov_b32 m0, s23
	v_lshl_add_u64 v[4:5], v[2:3], 0, s[24:25]
	s_mov_b32 s22, m0
	s_mov_b32 m0, s39
	s_nop 0
	global_load_lds_dword v[4:5], off
	s_mov_b32 m0, s22
	s_addk_i32 s10, 0x80
	s_add_i32 s17, s17, 0xa0000
	s_mul_hi_u32 s10, s10, 0x1400
	s_add_u32 s22, s84, s17
	s_addc_u32 s23, s85, s10
	v_lshl_add_u64 v[4:5], s[22:23], 0, v[64:65]
	v_lshl_add_u64 v[4:5], v[4:5], 0, s[78:79]
	s_mov_b32 s22, m0
	s_mov_b32 m0, s38
	s_nop 0
	global_load_lds_dwordx4 v[4:5], off
	s_mov_b32 m0, s22
	s_add_u32 s22, s30, s17
	s_addc_u32 s23, s31, s10
	v_lshl_add_u64 v[4:5], s[22:23], 0, v[64:65]
	s_mov_b32 s10, m0
	s_mov_b32 m0, s5
	s_nop 0
	global_load_lds_dwordx4 v[4:5], off
	s_mov_b32 m0, s10
	v_lshl_add_u64 v[2:3], v[2:3], 0, s[86:87]
	s_mov_b32 s5, m0
	s_mov_b32 m0, s4
	s_nop 0
	global_load_lds_dword v[2:3], off
	s_mov_b32 m0, s5
	v_lshlrev_b32_e32 v164, 7, v161
	v_bitop3_b32 v2, v18, v144, 7 bitop3:0x78
	v_add_u32_e32 v72, 0, v164
	v_lshlrev_b32_e32 v165, 4, v2
	s_waitcnt vmcnt(3) lgkmcnt(0)
	s_barrier
	v_lshlrev_b32_e32 v159, 4, v18
	v_readlane_b32 s4, v251, 14
	v_add_u32_e32 v2, v72, v165
	v_bfe_u32 v156, v144, 2, 2
	v_add_u32_e32 v0, s4, v159
	ds_read_b128 v[2:5], v2
	ds_read_b128 v[96:99], v0
	ds_read_b128 v[100:103], v0 offset:32
	ds_read_b128 v[104:107], v0 offset:64
	ds_read_b128 v[108:111], v0 offset:96
	v_add_u32_e32 v0, 2, v18
	v_bitop3_b32 v0, v0, v144, 7 bitop3:0x78
	v_lshlrev_b32_e32 v166, 4, v0
	v_add_u32_e32 v0, v72, v166
	s_setprio 1
	s_waitcnt lgkmcnt(0)
	v_mfma_f32_32x32x16_bf16 v[96:111], v[2:5], v[128:131], v[96:111]
	ds_read_b128 v[2:5], v0
	v_add_u32_e32 v0, 4, v18
	v_bitop3_b32 v0, v0, v144, 7 bitop3:0x78
	v_lshlrev_b32_e32 v160, 4, v0
	v_add_u32_e32 v0, v72, v160
	s_lshr_b32 s4, s82, 6
	v_bfe_u32 v157, v144, 4, 1
	s_waitcnt lgkmcnt(0)
	v_mfma_f32_32x32x16_bf16 v[96:111], v[2:5], v[140:143], v[96:111]
	ds_read_b128 v[2:5], v0
	v_add_u32_e32 v0, 6, v18
	v_bitop3_b32 v0, v0, v144, 7 bitop3:0x78
	v_lshlrev_b32_e32 v163, 4, v0
	v_add_u32_e32 v0, v72, v163
	v_and_b32_e32 v158, 3, v144
	v_or_b32_e32 v149, v148, v156
	s_waitcnt lgkmcnt(0)
	v_mfma_f32_32x32x16_bf16 v[96:111], v[2:5], v[136:139], v[96:111]
	ds_read_b128 v[2:5], v0
	s_mov_b32 s5, 0
	v_lshl_add_u64 v[152:153], s[30:31], 0, v[64:65]
	s_cmp_ge_u32 s96, s4
	v_lshl_add_u64 v[154:155], s[28:29], 0, v[6:7]
	s_waitcnt lgkmcnt(0)
	v_mfma_f32_32x32x16_bf16 v[96:111], v[2:5], v[132:135], v[96:111]
	s_setprio 0
	v_lshl_add_u64 v[2:3], s[84:85], 0, v[64:65]
	v_lshl_add_u64 v[150:151], v[2:3], 0, s[78:79]
	s_cbranch_scc1 .LBB0_321
	v_lshlrev_b32_e32 v0, 1, v157
	v_lshrrev_b32_e32 v2, 1, v158
	v_or_b32_e32 v3, v0, v2
	v_bitop3_b32 v0, v0, v149, v2 bitop3:0x36
	v_lshlrev_b32_e32 v4, 3, v144
	v_lshlrev_b32_e32 v76, 4, v0
	v_bitop3_b32 v0, v3, v149, 4 bitop3:0x36
	v_lshl_add_u64 v[2:3], v[154:155], 0, s[36:37]
	s_mov_b64 s[22:23], 0x300
	v_and_b32_e32 v4, 8, v4
	v_lshl_add_u64 v[66:67], v[2:3], 0, s[22:23]
	v_mad_u64_u32 v[2:3], s[22:23], s96, v223, v[152:153]
	s_mov_b64 s[38:39], 0xf0000
	v_add_u32_e32 v4, 0, v4
	v_add_lshl_u32 v5, v148, v156, 7
	v_lshl_add_u64 v[68:69], v[2:3], 0, s[38:39]
	v_mad_u64_u32 v[2:3], s[22:23], s96, v223, v[150:151]
	v_mov_b32_e32 v14, v1
	v_mov_b32_e32 v15, v1
	v_readlane_b32 s5, v251, 13
	v_lshlrev_b32_e32 v77, 4, v0
	v_lshl_add_u32 v78, v149, 7, v4
	v_add3_u32 v79, v5, v4, s21
	v_lshl_add_u64 v[70:71], v[2:3], 0, s[38:39]
	v_mov_b32_e32 v0, v1
	v_mov_b32_e32 v2, v1
	v_mov_b32_e32 v3, v1
	v_mov_b32_e32 v4, v1
	v_mov_b32_e32 v5, v1
	v_mov_b32_e32 v6, v1
	v_mov_b32_e32 v7, v1
	v_mov_b32_e32 v8, v1
	v_mov_b32_e32 v9, v1
	v_mov_b32_e32 v10, v1
	v_mov_b32_e32 v11, v1
	v_mov_b32_e32 v12, v1
	v_mov_b32_e32 v13, v1
	v_mov_b64_e32 v[94:95], v[14:15]
	v_cmp_gt_u32_e64 s[74:75], 32, v144
	v_lshl_add_u32 v73, v161, 2, s5
	v_lshl_add_u32 v74, v148, 2, s5
	v_add_u32_e32 v75, s19, v159
	v_mov_b32_e32 v16, v1
	v_mov_b32_e32 v17, v1
	v_mov_b32_e32 v18, v1
	v_mov_b32_e32 v19, v1
	v_mov_b32_e32 v20, v1
	v_mov_b32_e32 v21, v1
	v_mov_b32_e32 v22, v1
	v_mov_b32_e32 v23, v1
	v_mov_b32_e32 v24, v1
	v_mov_b32_e32 v25, v1
	v_mov_b32_e32 v26, v1
	v_mov_b32_e32 v27, v1
	v_mov_b32_e32 v28, v1
	v_mov_b32_e32 v29, v1
	v_mov_b32_e32 v30, v1
	v_mov_b32_e32 v31, v1
	v_mov_b32_e32 v32, v1
	v_mov_b32_e32 v33, v1
	v_mov_b32_e32 v34, v1
	v_mov_b32_e32 v35, v1
	v_mov_b32_e32 v36, v1
	v_mov_b32_e32 v37, v1
	v_mov_b32_e32 v38, v1
	v_mov_b32_e32 v39, v1
	v_mov_b32_e32 v40, v1
	v_mov_b32_e32 v41, v1
	v_mov_b32_e32 v42, v1
	v_mov_b32_e32 v43, v1
	v_mov_b32_e32 v44, v1
	v_mov_b32_e32 v45, v1
	v_mov_b32_e32 v46, v1
	v_mov_b32_e32 v47, v1
	s_mov_b32 s17, 0
	v_mov_b32_e32 v167, 0xff800000
	v_mov_b64_e32 v[92:93], v[12:13]
	v_mov_b64_e32 v[90:91], v[10:11]
	v_mov_b64_e32 v[88:89], v[8:9]
	v_mov_b64_e32 v[86:87], v[6:7]
	v_mov_b64_e32 v[84:85], v[4:5]
	v_mov_b64_e32 v[82:83], v[2:3]
	v_mov_b64_e32 v[80:81], v[0:1]
	s_mov_b32 s10, s96

.LBB0_300:
	v_lshl_add_u32 v0, s17, 13, v72
	s_or_b32 s5, s17, s95
	v_add_u32_e32 v2, v0, v165
	v_lshl_add_u32 v6, s5, 8, v75
	ds_read_b128 v[2:5], v2 offset:4096
	ds_read_b128 v[48:51], v6 offset:128
	ds_read_b128 v[52:55], v6 offset:160
	ds_read_b128 v[56:59], v6 offset:192
	ds_read_b128 v[60:63], v6 offset:224
	v_add_u32_e32 v6, v0, v166
	ds_read_b128 v[6:9], v6 offset:4096
	s_setprio 1
	s_waitcnt lgkmcnt(1)
	v_mfma_f32_32x32x16_bf16 v[48:63], v[2:5], v[128:131], v[48:63]
	v_add_u32_e32 v2, v0, v160
	ds_read_b128 v[2:5], v2 offset:4096
	v_add_u32_e32 v0, v0, v163
	v_max_f32_e32 v10, v96, v96
	s_waitcnt lgkmcnt(1)
	v_mfma_f32_32x32x16_bf16 v[48:63], v[6:9], v[140:143], v[48:63]
	ds_read_b128 v[6:9], v0 offset:4096
	v_max_f32_e32 v0, v97, v97
	v_max_f32_e32 v0, v10, v0
	v_max3_f32 v0, v0, v98, v99
	v_max3_f32 v0, v0, v100, v101
	v_max3_f32 v0, v0, v102, v103
	v_max3_f32 v0, v0, v104, v105
	s_waitcnt lgkmcnt(1)
	v_mfma_f32_32x32x16_bf16 v[48:63], v[2:5], v[136:139], v[48:63]
	v_max3_f32 v0, v0, v106, v107
	v_max3_f32 v0, v0, v108, v109
	v_max3_f32 v0, v0, v110, v111
	ds_bpermute_b32 v2, v147, v0
	s_waitcnt lgkmcnt(0)
	v_max_f32_e32 v2, v2, v2
	v_mfma_f32_32x32x16_bf16 v[48:63], v[6:9], v[132:135], v[48:63]
	s_setprio 0
	v_max_f32_e32 v0, v0, v2
	v_cmp_ge_f32_e32 vcc, v0, v162
	s_cbranch_vccz .LBB0_305
	v_add_f32_e32 v2, 0x41000000, v167
	v_cmp_gt_f32_e32 vcc, v0, v2
	s_cbranch_vccz .LBB0_306
	v_max_f32_e32 v0, v0, v0
	v_max_f32_e32 v2, v167, v167
	v_max_f32_e32 v0, v2, v0
	s_and_saveexec_b64 s[78:79], s[74:75]
	s_cbranch_execz .LBB0_304
	v_sub_f32_e32 v2, v167, v0
	v_exp_f32_e32 v2, v2
	ds_write_b32 v73, v2

.LBB0_307:
	v_sub_f32_e32 v2, v96, v0
	v_sub_f32_e32 v3, v97, v0
	v_sub_f32_e32 v4, v98, v0
	v_sub_f32_e32 v5, v99, v0
	v_sub_f32_e32 v6, v100, v0
	v_sub_f32_e32 v7, v101, v0
	v_sub_f32_e32 v8, v102, v0
	v_sub_f32_e32 v9, v103, v0
	v_exp_f32_e32 v2, v2
	v_exp_f32_e32 v3, v3
	v_exp_f32_e32 v4, v4
	v_exp_f32_e32 v5, v5
	v_exp_f32_e32 v6, v6
	v_exp_f32_e32 v7, v7
	v_exp_f32_e32 v8, v8
	v_exp_f32_e32 v9, v9
	v_lshl_add_u32 v98, s17, 14, v78
	v_add_u32_e32 v99, v98, v76
	v_cvt_pk_bf16_f32 v2, v2, v3
	v_cvt_pk_bf16_f32 v3, v4, v5
	v_cvt_pk_bf16_f32 v4, v6, v7
	v_cvt_pk_bf16_f32 v5, v8, v9
	ds_read_b64_tr_b16 v[6:7], v99 offset:32768
	ds_read_b64_tr_b16 v[8:9], v99 offset:33792
	v_add_u32_e32 v98, v98, v77
	s_waitcnt lgkmcnt(0)
	v_mfma_f32_32x32x16_bf16 v[16:31], v[2:5], v[6:9], v[16:31]
	ds_read_b64_tr_b16 v[6:7], v98 offset:32768
	ds_read_b64_tr_b16 v[8:9], v98 offset:33792
	v_sub_f32_e32 v10, v104, v0
	v_sub_f32_e32 v11, v105, v0
	v_sub_f32_e32 v12, v106, v0
	v_sub_f32_e32 v13, v107, v0
	v_sub_f32_e32 v14, v108, v0
	v_sub_f32_e32 v15, v109, v0
	v_sub_f32_e32 v96, v110, v0
	v_sub_f32_e32 v97, v111, v0
	v_exp_f32_e32 v10, v10
	v_exp_f32_e32 v11, v11
	v_exp_f32_e32 v12, v12
	v_exp_f32_e32 v13, v13
	v_exp_f32_e32 v14, v14
	v_exp_f32_e32 v15, v15
	v_exp_f32_e32 v96, v96
	v_exp_f32_e32 v97, v97
	s_mov_b32 s77, s76
	s_setprio 1
	s_waitcnt lgkmcnt(0)
	v_mfma_f32_32x32x16_bf16 v[32:47], v[2:5], v[6:9], v[32:47]
	s_mov_b32 s78, s76
	s_mov_b32 s79, s76
	v_mov_b64_e32 v[6:7], s[76:77]
	v_mov_b64_e32 v[8:9], s[78:79]
	s_movk_i32 s77, 0x110
	s_nop 0
	v_mfma_f32_32x32x16_bf16 v[80:95], v[2:5], v[6:9], v[80:95]
	v_cvt_pk_bf16_f32 v2, v10, v11
	v_cvt_pk_bf16_f32 v3, v12, v13
	v_cvt_pk_bf16_f32 v4, v14, v15
	v_cvt_pk_bf16_f32 v5, v96, v97
	ds_read_b64_tr_b16 v[10:11], v99 offset:34816
	ds_read_b64_tr_b16 v[12:13], v99 offset:35840
	s_waitcnt lgkmcnt(0)
	v_mfma_f32_32x32x16_bf16 v[16:31], v[2:5], v[10:13], v[16:31]
	ds_read_b64_tr_b16 v[10:11], v98 offset:34816
	ds_read_b64_tr_b16 v[12:13], v98 offset:35840
	s_waitcnt lgkmcnt(0)
	v_mfma_f32_32x32x16_bf16 v[32:47], v[2:5], v[10:13], v[32:47]
	v_mfma_f32_32x32x16_bf16 v[80:95], v[2:5], v[6:9], v[80:95]
	s_setprio 0
.LBB0_308:
	s_add_i32 s5, s17, 1
	s_and_b32 s5, s5, 3
	v_lshl_add_u32 v10, s5, 13, v72
	s_or_b32 s22, s5, s95
	v_add_u32_e32 v2, v10, v165
	v_lshl_add_u32 v6, s22, 8, v75
	ds_read_b128 v[2:5], v2
	ds_read_b128 v[96:99], v6
	ds_read_b128 v[100:103], v6 offset:32
	ds_read_b128 v[104:107], v6 offset:64
	ds_read_b128 v[108:111], v6 offset:96
	v_add_u32_e32 v6, v10, v166
	ds_read_b128 v[6:9], v6
	s_setprio 1
	s_waitcnt lgkmcnt(1)
	v_mfma_f32_32x32x16_bf16 v[96:111], v[2:5], v[128:131], v[96:111]
	v_add_u32_e32 v2, v10, v160
	ds_read_b128 v[2:5], v2
	v_max_f32_e32 v11, v48, v48
	s_waitcnt lgkmcnt(1)
	v_mfma_f32_32x32x16_bf16 v[96:111], v[6:9], v[140:143], v[96:111]
	v_add_u32_e32 v6, v10, v163
	ds_read_b128 v[6:9], v6
	v_max_f32_e32 v10, v49, v49
	v_max_f32_e32 v10, v11, v10
	v_max3_f32 v10, v10, v50, v51
	v_max3_f32 v10, v10, v52, v53
	s_waitcnt lgkmcnt(1)
	v_mfma_f32_32x32x16_bf16 v[96:111], v[2:5], v[136:139], v[96:111]
	v_max3_f32 v2, v10, v54, v55
	v_max3_f32 v2, v2, v56, v57
	v_max3_f32 v2, v2, v58, v59
	v_max3_f32 v2, v2, v60, v61
	v_max3_f32 v2, v2, v62, v63
	ds_bpermute_b32 v3, v147, v2
	s_waitcnt lgkmcnt(0)
	v_max_f32_e32 v3, v3, v3
	v_mfma_f32_32x32x16_bf16 v[96:111], v[6:9], v[132:135], v[96:111]
	s_setprio 0
	v_max_f32_e32 v2, v2, v3
	v_cmp_ge_f32_e32 vcc, v2, v162
	s_cbranch_vccz .LBB0_313
	v_add_f32_e32 v3, 0x41000000, v0
	v_cmp_gt_f32_e32 vcc, v2, v3
	s_cbranch_vccz .LBB0_314
	v_max_f32_e32 v2, v2, v2
	v_max_f32_e32 v3, v0, v0
	v_max_f32_e32 v167, v3, v2
	s_and_saveexec_b64 s[78:79], s[74:75]
	s_cbranch_execz .LBB0_312
	v_sub_f32_e32 v0, v0, v167
	v_exp_f32_e32 v0, v0
	ds_write_b32 v73, v0

.LBB0_315:
	v_sub_f32_e32 v9, v56, v167
	v_sub_f32_e32 v0, v48, v167
	v_sub_f32_e32 v2, v49, v167
	v_exp_f32_e32 v10, v9
	v_sub_f32_e32 v9, v57, v167
	v_exp_f32_e32 v0, v0
	v_exp_f32_e32 v2, v2
	v_exp_f32_e32 v11, v9
	v_sub_f32_e32 v9, v58, v167
	v_sub_f32_e32 v3, v50, v167
	v_sub_f32_e32 v4, v51, v167
	v_sub_f32_e32 v5, v52, v167
	v_sub_f32_e32 v6, v53, v167
	v_sub_f32_e32 v7, v54, v167
	v_sub_f32_e32 v8, v55, v167
	v_exp_f32_e32 v12, v9
	v_sub_f32_e32 v9, v59, v167
	v_exp_f32_e32 v3, v3
	v_exp_f32_e32 v4, v4
	v_exp_f32_e32 v5, v5
	v_exp_f32_e32 v6, v6
	v_exp_f32_e32 v7, v7
	v_exp_f32_e32 v8, v8
	v_exp_f32_e32 v13, v9
	v_sub_f32_e32 v9, v60, v167
	v_exp_f32_e32 v14, v9
	v_sub_f32_e32 v9, v61, v167
	v_exp_f32_e32 v15, v9
	v_sub_f32_e32 v9, v62, v167
	v_cvt_pk_bf16_f32 v2, v0, v2
	v_lshl_add_u32 v0, s17, 14, v79
	v_exp_f32_e32 v48, v9
	v_sub_f32_e32 v9, v63, v167
	v_add_u32_e32 v50, v0, v76
	v_exp_f32_e32 v49, v9
	v_cvt_pk_bf16_f32 v3, v3, v4
	v_cvt_pk_bf16_f32 v4, v5, v6
	v_cvt_pk_bf16_f32 v5, v7, v8
	ds_read_b64_tr_b16 v[6:7], v50 offset:32768
	ds_read_b64_tr_b16 v[8:9], v50 offset:33792
	v_add_u32_e32 v0, v0, v77
	s_setprio 1
	s_waitcnt lgkmcnt(0)
	v_mfma_f32_32x32x16_bf16 v[16:31], v[2:5], v[6:9], v[16:31]
	ds_read_b64_tr_b16 v[6:7], v0 offset:32768
	ds_read_b64_tr_b16 v[8:9], v0 offset:33792
	s_mov_b32 s77, s76
	s_mov_b32 s78, s76
	s_mov_b32 s79, s76
	s_waitcnt lgkmcnt(0)
	v_mfma_f32_32x32x16_bf16 v[32:47], v[2:5], v[6:9], v[32:47]
	v_mov_b64_e32 v[6:7], s[76:77]
	v_mov_b64_e32 v[8:9], s[78:79]
	s_movk_i32 s77, 0x110
	s_nop 0
	v_mfma_f32_32x32x16_bf16 v[80:95], v[2:5], v[6:9], v[80:95]
	v_cvt_pk_bf16_f32 v2, v10, v11
	v_cvt_pk_bf16_f32 v3, v12, v13
	v_cvt_pk_bf16_f32 v4, v14, v15
	v_cvt_pk_bf16_f32 v5, v48, v49
	ds_read_b64_tr_b16 v[10:11], v50 offset:34816
	ds_read_b64_tr_b16 v[12:13], v50 offset:35840
	s_waitcnt lgkmcnt(0)
	v_mfma_f32_32x32x16_bf16 v[16:31], v[2:5], v[10:13], v[16:31]
	ds_read_b64_tr_b16 v[10:11], v0 offset:34816
	ds_read_b64_tr_b16 v[12:13], v0 offset:35840
	s_waitcnt lgkmcnt(0)
	v_mfma_f32_32x32x16_bf16 v[32:47], v[2:5], v[10:13], v[32:47]
	v_mfma_f32_32x32x16_bf16 v[80:95], v[2:5], v[6:9], v[80:95]
	s_setprio 0
	s_mov_b64 s[78:79], -1
	s_and_b64 vcc, exec, s[90:91]
	s_cbranch_vccz .LBB0_317

.LBB0_334:
	v_sub_f32_e32 v11, v11, v169
	v_sub_f32_e32 v10, v10, v169
	v_sub_f32_e32 v13, v13, v169
	v_sub_f32_e32 v12, v12, v169
	v_exp_f32_e32 v11, v11
	v_exp_f32_e32 v10, v10
	v_sub_f32_e32 v168, v168, v169
	v_sub_f32_e32 v145, v145, v169
	v_sub_f32_e32 v15, v15, v169
	v_sub_f32_e32 v14, v14, v169
	v_exp_f32_e32 v13, v13
	v_exp_f32_e32 v12, v12
	v_sub_f32_e32 v4, v4, v169
	v_exp_f32_e32 v168, v168
	v_exp_f32_e32 v145, v145
	v_exp_f32_e32 v15, v15
	v_exp_f32_e32 v14, v14
	v_sub_f32_e32 v8, v8, v169
	v_sub_f32_e32 v6, v6, v169
	v_exp_f32_e32 v175, v4
	v_sub_f32_e32 v3, v3, v169
	v_sub_f32_e32 v2, v2, v169
	s_lshl_b32 s10, s5, 14
	v_lshlrev_b32_e32 v4, 3, v144
	v_sub_f32_e32 v9, v9, v169
	v_exp_f32_e32 v171, v8
	v_sub_f32_e32 v7, v7, v169
	v_exp_f32_e32 v173, v6
	v_sub_f32_e32 v5, v5, v169
	v_exp_f32_e32 v176, v3
	v_exp_f32_e32 v169, v2
	s_add_i32 s10, s10, 0
	v_lshlrev_b32_e32 v2, 1, v157
	v_lshrrev_b32_e32 v3, 1, v158
	v_and_b32_e32 v6, 8, v4
	v_lshlrev_b32_e32 v8, 7, v149
	v_exp_f32_e32 v172, v7
	v_exp_f32_e32 v174, v5
	v_bitop3_b32 v7, v2, v149, v3 bitop3:0x36
	v_cvt_pk_bf16_f32 v5, v11, v10
	v_add3_u32 v10, s10, v6, v8
	v_cvt_pk_bf16_f32 v4, v13, v12
	v_lshl_add_u32 v12, v7, 4, v10
	v_exp_f32_e32 v170, v9
	v_or_b32_e32 v177, v2, v3
	v_cvt_pk_bf16_f32 v2, v168, v145
	v_cvt_pk_bf16_f32 v3, v15, v14
	ds_read_b64_tr_b16 v[6:7], v12 offset:32768
	ds_read_b64_tr_b16 v[8:9], v12 offset:33792
	s_setprio 1
	s_waitcnt lgkmcnt(0)
	v_mfma_f32_32x32x16_bf16 v[48:63], v[2:5], v[6:9], v[48:63]
	v_bitop3_b32 v6, v177, v149, 4 bitop3:0x36
	v_lshl_add_u32 v14, v6, 4, v10
	ds_read_b64_tr_b16 v[6:7], v14 offset:32768
	ds_read_b64_tr_b16 v[8:9], v14 offset:33792
	s_mov_b32 s77, s76
	s_mov_b32 s78, s76
	s_mov_b32 s79, s76
	ds_read_b64_tr_b16 v[10:11], v12 offset:34816
	ds_read_b64_tr_b16 v[12:13], v12 offset:35840
	s_waitcnt lgkmcnt(2)
	v_mfma_f32_32x32x16_bf16 v[64:79], v[2:5], v[6:9], v[64:79]
	v_mov_b64_e32 v[6:7], s[76:77]
	v_mov_b64_e32 v[8:9], s[78:79]
	s_movk_i32 s77, 0x110
	s_nop 0
	v_mfma_f32_32x32x16_bf16 v[112:127], v[2:5], v[6:9], v[112:127]
	v_cvt_pk_bf16_f32 v2, v170, v171
	v_cvt_pk_bf16_f32 v3, v172, v173
	v_cvt_pk_bf16_f32 v4, v174, v175
	v_cvt_pk_bf16_f32 v5, v176, v169
	s_waitcnt lgkmcnt(0)
	s_nop 0
	v_mfma_f32_32x32x16_bf16 v[48:63], v[2:5], v[10:13], v[48:63]
	ds_read_b64_tr_b16 v[10:11], v14 offset:34816
	ds_read_b64_tr_b16 v[12:13], v14 offset:35840
	s_waitcnt lgkmcnt(0)
	v_mfma_f32_32x32x16_bf16 v[64:79], v[2:5], v[10:13], v[64:79]
	v_mfma_f32_32x32x16_bf16 v[112:127], v[2:5], v[6:9], v[112:127]
	s_setprio 0

.LBB0_336:
	s_lshl_b32 s10, s5, 13
	s_or_b32 s22, s5, s95
	s_add_i32 s17, s10, 0
	s_lshl_b32 s22, s22, 8
	v_add_u32_e32 v10, s17, v164
	s_add_i32 s22, s22, 0
	s_add_i32 s22, s22, 0x18000
	v_add_u32_e32 v2, v10, v165
	v_add_u32_e32 v6, s22, v159
	ds_read_b128 v[2:5], v2 offset:4096
	ds_read_b128 v[48:51], v6 offset:128
	ds_read_b128 v[52:55], v6 offset:160
	ds_read_b128 v[56:59], v6 offset:192
	ds_read_b128 v[60:63], v6 offset:224
	v_add_u32_e32 v6, v10, v166
	s_setprio 1
	s_waitcnt lgkmcnt(0)
	v_mfma_f32_32x32x16_bf16 v[48:63], v[2:5], v[128:131], v[48:63]
	ds_read_b128 v[2:5], v6 offset:4096
	v_add_u32_e32 v6, v10, v160
	ds_read_b128 v[6:9], v6 offset:4096
	v_max_f32_e32 v11, v96, v96
	s_waitcnt lgkmcnt(1)
	v_mfma_f32_32x32x16_bf16 v[48:63], v[2:5], v[140:143], v[48:63]
	v_add_u32_e32 v2, v10, v163
	ds_read_b128 v[2:5], v2 offset:4096
	v_max_f32_e32 v10, v97, v97
	v_max_f32_e32 v10, v11, v10
	v_max3_f32 v10, v10, v98, v99
	v_max3_f32 v10, v10, v100, v101
	s_waitcnt lgkmcnt(1)
	v_mfma_f32_32x32x16_bf16 v[48:63], v[6:9], v[136:139], v[48:63]
	v_max3_f32 v6, v10, v102, v103
	v_max3_f32 v6, v6, v104, v105
	v_max3_f32 v6, v6, v106, v107
	v_max3_f32 v6, v6, v108, v109
	v_max3_f32 v6, v6, v110, v111
	ds_bpermute_b32 v7, v147, v6
	s_waitcnt lgkmcnt(1)
	v_mfma_f32_32x32x16_bf16 v[48:63], v[2:5], v[132:135], v[48:63]
	s_setprio 0
	s_waitcnt lgkmcnt(0)
	v_max_f32_e32 v2, v7, v7
	v_max_f32_e32 v2, v6, v2
	v_cmp_ge_f32_e32 vcc, v2, v162
	s_cbranch_vccz .LBB0_341
	v_add_f32_e32 v3, 0x41000000, v167
	v_cmp_gt_f32_e32 vcc, v2, v3
	s_cbranch_vccz .LBB0_342
	v_max_f32_e32 v2, v2, v2
	v_max_f32_e32 v3, v167, v167
	v_max_f32_e32 v2, v3, v2
	v_cmp_gt_u32_e32 vcc, 32, v144
	s_and_saveexec_b64 s[28:29], vcc
	s_cbranch_execz .LBB0_340
	v_sub_f32_e32 v3, v167, v2
	v_exp_f32_e32 v3, v3
	v_readlane_b32 s22, v251, 13
	s_nop 1
	v_lshl_add_u32 v4, v161, 2, s22
	ds_write_b32 v4, v3

.LBB0_343:
	v_sub_f32_e32 v11, v104, v2
	v_exp_f32_e32 v12, v11
	v_sub_f32_e32 v11, v105, v2
	v_exp_f32_e32 v13, v11
	v_sub_f32_e32 v11, v106, v2
	v_sub_f32_e32 v3, v96, v2
	v_sub_f32_e32 v4, v97, v2
	v_exp_f32_e32 v14, v11
	v_sub_f32_e32 v11, v107, v2
	v_exp_f32_e32 v3, v3
	v_exp_f32_e32 v4, v4
	v_exp_f32_e32 v15, v11
	v_sub_f32_e32 v11, v108, v2
	v_exp_f32_e32 v64, v11
	v_sub_f32_e32 v11, v109, v2
	v_sub_f32_e32 v5, v98, v2
	v_sub_f32_e32 v6, v99, v2
	v_sub_f32_e32 v7, v100, v2
	v_sub_f32_e32 v8, v101, v2
	v_sub_f32_e32 v9, v102, v2
	v_sub_f32_e32 v10, v103, v2
	v_exp_f32_e32 v65, v11
	v_sub_f32_e32 v11, v110, v2
	v_exp_f32_e32 v5, v5
	v_exp_f32_e32 v6, v6
	v_exp_f32_e32 v7, v7
	v_exp_f32_e32 v8, v8
	v_exp_f32_e32 v9, v9
	v_exp_f32_e32 v10, v10
	v_exp_f32_e32 v66, v11
	v_sub_f32_e32 v11, v111, v2
	s_lshl_b32 s22, s5, 14
	v_lshlrev_b32_e32 v70, 3, v144
	v_exp_f32_e32 v67, v11
	s_add_i32 s22, s22, 0
	v_lshlrev_b32_e32 v11, 1, v157
	v_lshrrev_b32_e32 v68, 1, v158
	v_and_b32_e32 v70, 8, v70
	v_cvt_pk_bf16_f32 v4, v3, v4
	v_lshlrev_b32_e32 v3, 7, v149
	v_or_b32_e32 v69, v11, v68
	v_bitop3_b32 v11, v11, v149, v68 bitop3:0x36
	v_add3_u32 v3, s22, v70, v3
	v_lshl_add_u32 v68, v11, 4, v3
	v_cvt_pk_bf16_f32 v5, v5, v6
	v_cvt_pk_bf16_f32 v6, v7, v8
	v_cvt_pk_bf16_f32 v7, v9, v10
	ds_read_b64_tr_b16 v[8:9], v68 offset:32768
	ds_read_b64_tr_b16 v[10:11], v68 offset:33792
	s_setprio 1
	s_waitcnt lgkmcnt(0)
	v_mfma_f32_32x32x16_bf16 v[16:31], v[4:7], v[8:11], v[16:31]
	v_bitop3_b32 v8, v69, v149, 4 bitop3:0x36
	v_lshl_add_u32 v3, v8, 4, v3
	ds_read_b64_tr_b16 v[8:9], v3 offset:32768
	ds_read_b64_tr_b16 v[10:11], v3 offset:33792
	s_mov_b32 s77, s76
	s_mov_b32 s78, s76
	s_mov_b32 s79, s76
	s_waitcnt lgkmcnt(0)
	v_mfma_f32_32x32x16_bf16 v[32:47], v[4:7], v[8:11], v[32:47]
	v_mov_b64_e32 v[8:9], s[76:77]
	v_mov_b64_e32 v[10:11], s[78:79]
	s_movk_i32 s77, 0x110
	s_nop 0
	v_mfma_f32_32x32x16_bf16 v[80:95], v[4:7], v[8:11], v[80:95]
	v_cvt_pk_bf16_f32 v4, v12, v13
	v_cvt_pk_bf16_f32 v5, v14, v15
	v_cvt_pk_bf16_f32 v6, v64, v65
	v_cvt_pk_bf16_f32 v7, v66, v67
	ds_read_b64_tr_b16 v[12:13], v68 offset:34816
	ds_read_b64_tr_b16 v[14:15], v68 offset:35840
	s_waitcnt lgkmcnt(0)
	v_mfma_f32_32x32x16_bf16 v[16:31], v[4:7], v[12:15], v[16:31]
	ds_read_b64_tr_b16 v[12:13], v3 offset:34816
	ds_read_b64_tr_b16 v[14:15], v3 offset:35840
	s_waitcnt lgkmcnt(0)
	v_mfma_f32_32x32x16_bf16 v[32:47], v[4:7], v[12:15], v[32:47]
	v_mfma_f32_32x32x16_bf16 v[80:95], v[4:7], v[8:11], v[80:95]
	s_setprio 0

.LBB0_350:
	v_sub_f32_e32 v12, v12, v50
	v_sub_f32_e32 v11, v11, v50
	v_exp_f32_e32 v12, v12
	v_exp_f32_e32 v11, v11
	v_sub_f32_e32 v5, v5, v50
	v_sub_f32_e32 v2, v64, v50
	v_sub_f32_e32 v49, v49, v50
	v_sub_f32_e32 v48, v48, v50
	v_sub_f32_e32 v15, v15, v50
	v_sub_f32_e32 v14, v14, v50
	v_sub_f32_e32 v13, v13, v50
	v_exp_f32_e32 v55, v5
	v_lshlrev_b32_e32 v5, 3, v144
	v_exp_f32_e32 v2, v2
	v_exp_f32_e32 v49, v49
	v_exp_f32_e32 v48, v48
	v_exp_f32_e32 v15, v15
	v_exp_f32_e32 v14, v14
	v_exp_f32_e32 v13, v13
	v_sub_f32_e32 v7, v7, v50
	v_sub_f32_e32 v6, v6, v50
	v_sub_f32_e32 v4, v4, v50
	v_sub_f32_e32 v3, v3, v50
	s_add_i32 s17, s17, s10
	v_and_b32_e32 v5, 8, v5
	v_sub_f32_e32 v10, v10, v50
	v_sub_f32_e32 v9, v9, v50
	v_sub_f32_e32 v8, v8, v50
	v_exp_f32_e32 v53, v7
	v_exp_f32_e32 v54, v6
	v_exp_f32_e32 v56, v4
	v_exp_f32_e32 v50, v3
	v_add_lshl_u32 v6, v148, v156, 7
	v_lshlrev_b32_e32 v3, 1, v157
	v_lshrrev_b32_e32 v4, 1, v158
	v_add_u32_e32 v7, s17, v5
	v_exp_f32_e32 v52, v8
	v_bitop3_b32 v8, v3, v149, v4 bitop3:0x36
	v_cvt_pk_bf16_f32 v5, v12, v11
	v_add3_u32 v11, v6, v7, s21
	v_lshl_add_u32 v12, v8, 4, v11
	v_exp_f32_e32 v51, v9
	v_or_b32_e32 v57, v3, v4
	v_cvt_pk_bf16_f32 v2, v2, v49
	v_cvt_pk_bf16_f32 v3, v48, v15
	v_cvt_pk_bf16_f32 v4, v14, v13
	ds_read_b64_tr_b16 v[6:7], v12 offset:32768
	ds_read_b64_tr_b16 v[8:9], v12 offset:33792
	s_setprio 1
	s_waitcnt lgkmcnt(0)
	v_mfma_f32_32x32x16_bf16 v[16:31], v[2:5], v[6:9], v[16:31]
	v_bitop3_b32 v6, v57, v149, 4 bitop3:0x36
	v_lshl_add_u32 v14, v6, 4, v11
	ds_read_b64_tr_b16 v[6:7], v14 offset:32768
	ds_read_b64_tr_b16 v[8:9], v14 offset:33792
	v_exp_f32_e32 v10, v10
	s_mov_b32 s77, s76
	s_mov_b32 s78, s76
	s_mov_b32 s79, s76
	s_waitcnt lgkmcnt(0)
	v_mfma_f32_32x32x16_bf16 v[32:47], v[2:5], v[6:9], v[32:47]
	v_mov_b64_e32 v[6:7], s[76:77]
	v_mov_b64_e32 v[8:9], s[78:79]
	s_movk_i32 s77, 0x110
	s_nop 0
	v_mfma_f32_32x32x16_bf16 v[80:95], v[2:5], v[6:9], v[80:95]
	v_cvt_pk_bf16_f32 v2, v10, v51
	v_cvt_pk_bf16_f32 v3, v52, v53
	v_cvt_pk_bf16_f32 v4, v54, v55
	v_cvt_pk_bf16_f32 v5, v56, v50
	ds_read_b64_tr_b16 v[10:11], v12 offset:34816
	ds_read_b64_tr_b16 v[12:13], v12 offset:35840
	s_waitcnt lgkmcnt(0)
	v_mfma_f32_32x32x16_bf16 v[16:31], v[2:5], v[10:13], v[16:31]
	ds_read_b64_tr_b16 v[10:11], v14 offset:34816
	ds_read_b64_tr_b16 v[12:13], v14 offset:35840
	s_waitcnt lgkmcnt(0)
	v_mfma_f32_32x32x16_bf16 v[32:47], v[2:5], v[10:13], v[32:47]
	v_mfma_f32_32x32x16_bf16 v[80:95], v[2:5], v[6:9], v[80:95]
	s_setprio 0
